# 4-segment + LDS-address GEMM loops plus: down-projection DMA addresses in saddr form, m0-hazard nops replaced by scalar work, MFMA clusters 8-byte aligned
# speedup vs baseline: 1.0028x; 1.0006x over previous
.LBB0_37:
	s_add_i32 s69, s48, 2
	s_add_u32 s46, s0, 0x100
	s_addc_u32 s47, s1, 0
	s_add_i32 s70, 0, 0x10000
	ds_read_b128 v[140:143], v153
	ds_read_b128 v[144:147], v153 offset:1024
	ds_read_b128 v[148:151], v153 offset:2048
	ds_read_b128 v[168:171], v153 offset:3072
	s_cmp_eq_u32 s12, s48
	s_cselect_b32 s48, s44, s13
	s_cselect_b32 s51, s43, s47
	s_cselect_b32 s50, s42, s46
	s_cselect_b32 s49, s45, s68
	ds_read_b128 v[172:175], v155
	ds_read_b128 v[176:179], v155 offset:1024
	ds_read_b128 v[180:183], v155 offset:2048
	ds_read_b128 v[184:187], v155 offset:3072
	ds_read_b128 v[188:191], v155 offset:4096
	ds_read_b128 v[192:195], v155 offset:5120
	ds_read_b128 v[196:199], v155 offset:6144
	ds_read_b128 v[224:227], v155 offset:7168
	s_add_i32 m0, s53, 0xc000
	s_nop 0
	global_load_lds_dwordx4 v136, s[0:1]
	s_add_i32 m0, s53, 0xe000
	s_add_i32 s71, 0, 0x14000
	global_load_lds_dwordx4 v138, s[0:1]
	s_add_i32 s0, s70, s52
	ds_read_b128 v[228:231], v153 offset:16384
	ds_read_b128 v[232:235], v153 offset:17408
	ds_read_b128 v[236:239], v153 offset:18432
	ds_read_b128 v[240:243], v153 offset:19456
	s_waitcnt lgkmcnt(0)
	s_barrier
	v_mfma_f32_16x16x32_bf16 v[126:129], v[140:143], v[172:175], v[126:129]
	v_mfma_f32_16x16x32_bf16 v[122:125], v[148:151], v[172:175], v[122:125]
	v_mfma_f32_16x16x32_bf16 v[110:113], v[140:143], v[180:183], v[110:113]
	v_mfma_f32_16x16x32_bf16 v[106:109], v[148:151], v[180:183], v[106:109]
	v_mfma_f32_16x16x32_bf16 v[94:97], v[140:143], v[188:191], v[94:97]
	v_mfma_f32_16x16x32_bf16 v[90:93], v[148:151], v[188:191], v[90:93]
	v_mfma_f32_16x16x32_bf16 v[78:81], v[140:143], v[196:199], v[78:81]
	v_mfma_f32_16x16x32_bf16 v[74:77], v[148:151], v[196:199], v[74:77]
	v_mfma_f32_16x16x32_bf16 v[126:129], v[144:147], v[176:179], v[126:129]
	v_mfma_f32_16x16x32_bf16 v[122:125], v[168:171], v[176:179], v[122:125]
	v_mfma_f32_16x16x32_bf16 v[110:113], v[144:147], v[184:187], v[110:113]
	v_mfma_f32_16x16x32_bf16 v[106:109], v[168:171], v[184:187], v[106:109]
	v_mfma_f32_16x16x32_bf16 v[94:97], v[144:147], v[192:195], v[94:97]
	v_mfma_f32_16x16x32_bf16 v[90:93], v[168:171], v[192:195], v[90:93]
	v_mfma_f32_16x16x32_bf16 v[78:81], v[144:147], v[224:227], v[78:81]
	v_mfma_f32_16x16x32_bf16 v[74:77], v[168:171], v[224:227], v[74:77]
	v_mfma_f32_16x16x32_bf16 v[118:121], v[228:231], v[172:175], v[118:121]
	v_mfma_f32_16x16x32_bf16 v[114:117], v[236:239], v[172:175], v[114:117]
	v_mfma_f32_16x16x32_bf16 v[102:105], v[228:231], v[180:183], v[102:105]
	v_mfma_f32_16x16x32_bf16 v[98:101], v[236:239], v[180:183], v[98:101]
	v_mfma_f32_16x16x32_bf16 v[86:89], v[228:231], v[188:191], v[86:89]
	v_mfma_f32_16x16x32_bf16 v[82:85], v[236:239], v[188:191], v[82:85]
	v_mfma_f32_16x16x32_bf16 v[70:73], v[228:231], v[196:199], v[70:73]
	v_mfma_f32_16x16x32_bf16 v[66:69], v[236:239], v[196:199], v[66:69]
	v_mfma_f32_16x16x32_bf16 v[118:121], v[232:235], v[176:179], v[118:121]
	v_mfma_f32_16x16x32_bf16 v[114:117], v[240:243], v[176:179], v[114:117]
	v_mfma_f32_16x16x32_bf16 v[102:105], v[232:235], v[184:187], v[102:105]
	v_mfma_f32_16x16x32_bf16 v[98:101], v[240:243], v[184:187], v[98:101]
	v_mfma_f32_16x16x32_bf16 v[86:89], v[232:235], v[192:195], v[86:89]
	v_mfma_f32_16x16x32_bf16 v[82:85], v[240:243], v[192:195], v[82:85]
	v_mfma_f32_16x16x32_bf16 v[70:73], v[232:235], v[224:227], v[70:73]
	v_mfma_f32_16x16x32_bf16 v[66:69], v[240:243], v[224:227], v[66:69]
	s_barrier
	s_mov_b32 m0, s53
	s_add_u32 s78, s50, s94
	s_addc_u32 s79, s51, s95
	ds_read_b128 v[172:175], v155 offset:16384
	ds_read_b128 v[176:179], v155 offset:17408
	ds_read_b128 v[180:183], v155 offset:18432
	ds_read_b128 v[184:187], v155 offset:19456
	ds_read_b128 v[188:191], v155 offset:20480
	ds_read_b128 v[192:195], v155 offset:21504
	ds_read_b128 v[196:199], v155 offset:22528
	ds_read_b128 v[224:227], v155 offset:23552
	global_load_lds_dwordx4 v134, s[50:51]
	s_mov_b32 m0, s54
	s_add_u32 s76, s48, s94
	s_addc_u32 s77, s49, s95
	global_load_lds_dwordx4 v132, s[50:51]
	s_mov_b32 m0, s0
	s_nop 0
	global_load_lds_dwordx4 v0, s[48:49]
	s_add_i32 m0, s0, 0x2000
	s_add_u32 s0, s48, 0x160000
	s_addc_u32 s1, s49, 0
	global_load_lds_dwordx4 v130, s[48:49]
	s_add_i32 s70, s71, s52
	s_mov_b32 m0, s70
	s_nop 0
	global_load_lds_dwordx4 v0, s[0:1]
	s_add_i32 m0, s70, 0x2000
	s_nop 0
	global_load_lds_dwordx4 v130, s[0:1]
	s_waitcnt vmcnt(6) lgkmcnt(0)
	s_barrier
	v_mfma_f32_16x16x32_bf16 v[62:65], v[140:143], v[172:175], v[62:65]
	v_mfma_f32_16x16x32_bf16 v[58:61], v[148:151], v[172:175], v[58:61]
	v_mfma_f32_16x16x32_bf16 v[46:49], v[140:143], v[180:183], v[46:49]
	v_mfma_f32_16x16x32_bf16 v[42:45], v[148:151], v[180:183], v[42:45]
	v_mfma_f32_16x16x32_bf16 v[30:33], v[140:143], v[188:191], v[30:33]
	v_mfma_f32_16x16x32_bf16 v[26:29], v[148:151], v[188:191], v[26:29]
	v_mfma_f32_16x16x32_bf16 v[14:17], v[140:143], v[196:199], v[14:17]
	v_mfma_f32_16x16x32_bf16 v[10:13], v[148:151], v[196:199], v[10:13]
	v_mfma_f32_16x16x32_bf16 v[62:65], v[144:147], v[176:179], v[62:65]
	v_mfma_f32_16x16x32_bf16 v[58:61], v[168:171], v[176:179], v[58:61]
	v_mfma_f32_16x16x32_bf16 v[46:49], v[144:147], v[184:187], v[46:49]
	v_mfma_f32_16x16x32_bf16 v[42:45], v[168:171], v[184:187], v[42:45]
	v_mfma_f32_16x16x32_bf16 v[30:33], v[144:147], v[192:195], v[30:33]
	v_mfma_f32_16x16x32_bf16 v[26:29], v[168:171], v[192:195], v[26:29]
	v_mfma_f32_16x16x32_bf16 v[14:17], v[144:147], v[224:227], v[14:17]
	v_mfma_f32_16x16x32_bf16 v[10:13], v[168:171], v[224:227], v[10:13]
	v_mfma_f32_16x16x32_bf16 v[54:57], v[228:231], v[172:175], v[54:57]
	v_mfma_f32_16x16x32_bf16 v[50:53], v[236:239], v[172:175], v[50:53]
	v_mfma_f32_16x16x32_bf16 v[38:41], v[228:231], v[180:183], v[38:41]
	v_mfma_f32_16x16x32_bf16 v[34:37], v[236:239], v[180:183], v[34:37]
	v_mfma_f32_16x16x32_bf16 v[22:25], v[228:231], v[188:191], v[22:25]
	v_mfma_f32_16x16x32_bf16 v[18:21], v[236:239], v[188:191], v[18:21]
	v_mfma_f32_16x16x32_bf16 v[6:9], v[228:231], v[196:199], v[6:9]
	v_mfma_f32_16x16x32_bf16 v[2:5], v[236:239], v[196:199], v[2:5]
	v_mfma_f32_16x16x32_bf16 v[54:57], v[232:235], v[176:179], v[54:57]
	v_mfma_f32_16x16x32_bf16 v[50:53], v[240:243], v[176:179], v[50:53]
	v_mfma_f32_16x16x32_bf16 v[38:41], v[232:235], v[184:187], v[38:41]
	v_mfma_f32_16x16x32_bf16 v[34:37], v[240:243], v[184:187], v[34:37]
	v_mfma_f32_16x16x32_bf16 v[22:25], v[232:235], v[192:195], v[22:25]
	v_mfma_f32_16x16x32_bf16 v[18:21], v[240:243], v[192:195], v[18:21]
	v_mfma_f32_16x16x32_bf16 v[6:9], v[232:235], v[224:227], v[6:9]
	v_mfma_f32_16x16x32_bf16 v[2:5], v[240:243], v[224:227], v[2:5]
	s_barrier
	s_add_i32 s70, 0, 0x18000
	ds_read_b128 v[140:143], v153 offset:32768
	ds_read_b128 v[144:147], v153 offset:33792
	ds_read_b128 v[148:151], v153 offset:34816
	ds_read_b128 v[168:171], v153 offset:35840
	s_add_u32 s0, s50, 0x2c0000
	s_addc_u32 s1, s51, 0
	ds_read_b128 v[172:175], v155 offset:32768
	ds_read_b128 v[176:179], v155 offset:33792
	ds_read_b128 v[180:183], v155 offset:34816
	ds_read_b128 v[184:187], v155 offset:35840
	ds_read_b128 v[188:191], v155 offset:36864
	ds_read_b128 v[192:195], v155 offset:37888
	ds_read_b128 v[196:199], v155 offset:38912
	ds_read_b128 v[224:227], v155 offset:39936
	s_mov_b32 m0, s55
	s_nop 0
	global_load_lds_dwordx4 v134, s[0:1]
	s_mov_b32 m0, s56
	s_add_i32 s50, 0, 0x1c000
	global_load_lds_dwordx4 v132, s[0:1]
	s_add_i32 s0, s70, s52
	ds_read_b128 v[228:231], v153 offset:49152
	ds_read_b128 v[232:235], v153 offset:50176
	ds_read_b128 v[236:239], v153 offset:51200
	ds_read_b128 v[240:243], v153 offset:52224
	s_waitcnt lgkmcnt(0)
	s_barrier
	v_mfma_f32_16x16x32_bf16 v[126:129], v[140:143], v[172:175], v[126:129]
	v_mfma_f32_16x16x32_bf16 v[122:125], v[148:151], v[172:175], v[122:125]
	v_mfma_f32_16x16x32_bf16 v[110:113], v[140:143], v[180:183], v[110:113]
	v_mfma_f32_16x16x32_bf16 v[106:109], v[148:151], v[180:183], v[106:109]
	v_mfma_f32_16x16x32_bf16 v[94:97], v[140:143], v[188:191], v[94:97]
	v_mfma_f32_16x16x32_bf16 v[90:93], v[148:151], v[188:191], v[90:93]
	v_mfma_f32_16x16x32_bf16 v[78:81], v[140:143], v[196:199], v[78:81]
	v_mfma_f32_16x16x32_bf16 v[74:77], v[148:151], v[196:199], v[74:77]
	v_mfma_f32_16x16x32_bf16 v[126:129], v[144:147], v[176:179], v[126:129]
	v_mfma_f32_16x16x32_bf16 v[122:125], v[168:171], v[176:179], v[122:125]
	v_mfma_f32_16x16x32_bf16 v[110:113], v[144:147], v[184:187], v[110:113]
	v_mfma_f32_16x16x32_bf16 v[106:109], v[168:171], v[184:187], v[106:109]
	v_mfma_f32_16x16x32_bf16 v[94:97], v[144:147], v[192:195], v[94:97]
	v_mfma_f32_16x16x32_bf16 v[90:93], v[168:171], v[192:195], v[90:93]
	v_mfma_f32_16x16x32_bf16 v[78:81], v[144:147], v[224:227], v[78:81]
	v_mfma_f32_16x16x32_bf16 v[74:77], v[168:171], v[224:227], v[74:77]
	v_mfma_f32_16x16x32_bf16 v[118:121], v[228:231], v[172:175], v[118:121]
	v_mfma_f32_16x16x32_bf16 v[114:117], v[236:239], v[172:175], v[114:117]
	v_mfma_f32_16x16x32_bf16 v[102:105], v[228:231], v[180:183], v[102:105]
	v_mfma_f32_16x16x32_bf16 v[98:101], v[236:239], v[180:183], v[98:101]
	v_mfma_f32_16x16x32_bf16 v[86:89], v[228:231], v[188:191], v[86:89]
	v_mfma_f32_16x16x32_bf16 v[82:85], v[236:239], v[188:191], v[82:85]
	v_mfma_f32_16x16x32_bf16 v[70:73], v[228:231], v[196:199], v[70:73]
	v_mfma_f32_16x16x32_bf16 v[66:69], v[236:239], v[196:199], v[66:69]
	v_mfma_f32_16x16x32_bf16 v[118:121], v[232:235], v[176:179], v[118:121]
	v_mfma_f32_16x16x32_bf16 v[114:117], v[240:243], v[176:179], v[114:117]
	v_mfma_f32_16x16x32_bf16 v[102:105], v[232:235], v[184:187], v[102:105]
	v_mfma_f32_16x16x32_bf16 v[98:101], v[240:243], v[184:187], v[98:101]
	v_mfma_f32_16x16x32_bf16 v[86:89], v[232:235], v[192:195], v[86:89]
	v_mfma_f32_16x16x32_bf16 v[82:85], v[240:243], v[192:195], v[82:85]
	v_mfma_f32_16x16x32_bf16 v[70:73], v[232:235], v[224:227], v[70:73]
	v_mfma_f32_16x16x32_bf16 v[66:69], v[240:243], v[224:227], v[66:69]
	s_barrier
	s_mov_b32 m0, s57
	ds_read_b128 v[172:175], v155 offset:49152
	ds_read_b128 v[176:179], v155 offset:50176
	ds_read_b128 v[180:183], v155 offset:51200
	ds_read_b128 v[184:187], v155 offset:52224
	ds_read_b128 v[188:191], v155 offset:53248
	ds_read_b128 v[192:195], v155 offset:54272
	ds_read_b128 v[196:199], v155 offset:55296
	ds_read_b128 v[224:227], v155 offset:56320
	global_load_lds_dwordx4 v134, s[78:79]
	s_mov_b32 m0, s58
	s_nop 0
	global_load_lds_dwordx4 v132, s[78:79]
	s_mov_b32 m0, s0
	s_nop 0
	global_load_lds_dwordx4 v0, s[76:77]
	s_add_i32 m0, s0, 0x2000
	s_add_u32 s0, s48, 0x160080
	s_addc_u32 s1, s49, 0
	global_load_lds_dwordx4 v130, s[76:77]
	s_add_i32 s48, s50, s52
	s_mov_b32 m0, s48
	s_nop 0
	global_load_lds_dwordx4 v0, s[0:1]
	s_add_i32 m0, s48, 0x2000
	s_nop 0
	global_load_lds_dwordx4 v130, s[0:1]
	s_waitcnt vmcnt(6) lgkmcnt(0)
	s_nop 0
	s_barrier
	v_mfma_f32_16x16x32_bf16 v[62:65], v[140:143], v[172:175], v[62:65]
	v_mfma_f32_16x16x32_bf16 v[58:61], v[148:151], v[172:175], v[58:61]
	v_mfma_f32_16x16x32_bf16 v[46:49], v[140:143], v[180:183], v[46:49]
	v_mfma_f32_16x16x32_bf16 v[42:45], v[148:151], v[180:183], v[42:45]
	v_mfma_f32_16x16x32_bf16 v[30:33], v[140:143], v[188:191], v[30:33]
	v_mfma_f32_16x16x32_bf16 v[26:29], v[148:151], v[188:191], v[26:29]
	v_mfma_f32_16x16x32_bf16 v[14:17], v[140:143], v[196:199], v[14:17]
	v_mfma_f32_16x16x32_bf16 v[10:13], v[148:151], v[196:199], v[10:13]
	v_mfma_f32_16x16x32_bf16 v[62:65], v[144:147], v[176:179], v[62:65]
	v_mfma_f32_16x16x32_bf16 v[58:61], v[168:171], v[176:179], v[58:61]
	v_mfma_f32_16x16x32_bf16 v[46:49], v[144:147], v[184:187], v[46:49]
	v_mfma_f32_16x16x32_bf16 v[42:45], v[168:171], v[184:187], v[42:45]
	v_mfma_f32_16x16x32_bf16 v[30:33], v[144:147], v[192:195], v[30:33]
	v_mfma_f32_16x16x32_bf16 v[26:29], v[168:171], v[192:195], v[26:29]
	v_mfma_f32_16x16x32_bf16 v[14:17], v[144:147], v[224:227], v[14:17]
	v_mfma_f32_16x16x32_bf16 v[10:13], v[168:171], v[224:227], v[10:13]
	v_mfma_f32_16x16x32_bf16 v[54:57], v[228:231], v[172:175], v[54:57]
	v_mfma_f32_16x16x32_bf16 v[50:53], v[236:239], v[172:175], v[50:53]
	v_mfma_f32_16x16x32_bf16 v[38:41], v[228:231], v[180:183], v[38:41]
	v_mfma_f32_16x16x32_bf16 v[34:37], v[236:239], v[180:183], v[34:37]
	v_mfma_f32_16x16x32_bf16 v[22:25], v[228:231], v[188:191], v[22:25]
	v_mfma_f32_16x16x32_bf16 v[18:21], v[236:239], v[188:191], v[18:21]
	v_mfma_f32_16x16x32_bf16 v[6:9], v[228:231], v[196:199], v[6:9]
	v_mfma_f32_16x16x32_bf16 v[2:5], v[236:239], v[196:199], v[2:5]
	v_mfma_f32_16x16x32_bf16 v[54:57], v[232:235], v[176:179], v[54:57]
	v_mfma_f32_16x16x32_bf16 v[50:53], v[240:243], v[176:179], v[50:53]
	v_mfma_f32_16x16x32_bf16 v[38:41], v[232:235], v[184:187], v[38:41]
	v_mfma_f32_16x16x32_bf16 v[34:37], v[240:243], v[184:187], v[34:37]
	v_mfma_f32_16x16x32_bf16 v[22:25], v[232:235], v[192:195], v[22:25]
	v_mfma_f32_16x16x32_bf16 v[18:21], v[240:243], v[192:195], v[18:21]
	v_mfma_f32_16x16x32_bf16 v[6:9], v[232:235], v[224:227], v[6:9]
	v_mfma_f32_16x16x32_bf16 v[2:5], v[240:243], v[224:227], v[2:5]
	s_barrier
	s_add_u32 s13, s13, 0x100
	s_addc_u32 s68, s68, 0
	s_mov_b64 s[0:1], s[46:47]
	s_mov_b32 s48, s69
	s_cmp_ge_i32 s69, s39
	s_cbranch_scc0 .LBB0_37
	s_cmp_eq_u32 s65, 2
	s_cbranch_scc1 .Lepi10_orig
	v_readlane_b32 s90, v255, 17
	v_readlane_b32 s91, v255, 18
	v_readlane_b32 s96, v255, 19
	v_readlane_b32 s97, v255, 20
	v_lshl_or_b32 v156, s66, 8, v154
	v_lshlrev_b32_e32 v156, 2, v156
	v_lshl_add_u32 v157, v152, 13, v156
	s_lshl_b32 s72, s67, 21
	s_add_u32 s74, s22, s72
	s_addc_u32 s75, s23, 0
	s_add_u32 s76, s22, s72
	s_addc_u32 s77, s23, 0
	s_lshr_b32 s73, s67, 3
	s_mul_i32 s73, s73, 0xc000
	s_add_u32 s73, s73, 0xa000
	s_add_u32 s70, s90, s73
	s_addc_u32 s71, s91, 0
	global_load_dwordx4 v[140:143], v156, s[70:71]
	global_load_dwordx4 v[144:147], v156, s[70:71] offset:64
	global_load_dwordx4 v[148:151], v156, s[70:71] offset:512
	global_load_dwordx4 v[168:171], v156, s[70:71] offset:576
	global_load_dwordx4 v[224:227], v157, s[74:75] nt
	global_load_dwordx4 v[228:231], v157, s[74:75] offset:64 nt
	global_load_dwordx4 v[232:235], v157, s[74:75] offset:512 nt
	global_load_dwordx4 v[236:239], v157, s[74:75] offset:576 nt
	s_add_u32 s74, s74, 0x20000
	s_addc_u32 s75, s75, 0
	global_load_dwordx4 v[240:243], v157, s[74:75] nt
	global_load_dwordx4 v[244:247], v157, s[74:75] offset:64 nt
	s_waitcnt vmcnt(5)
	v_pk_fma_f32 v[128:129], v[128:129], v[142:143], v[226:227]
	v_pk_fma_f32 v[126:127], v[126:127], v[140:141], v[224:225]
	global_store_dwordx4 v157, v[126:129], s[76:77] nt
	global_load_dwordx4 v[224:227], v157, s[74:75] offset:512 nt
	s_waitcnt vmcnt(6)
	v_pk_fma_f32 v[124:125], v[124:125], v[146:147], v[230:231]
	v_pk_fma_f32 v[122:123], v[122:123], v[144:145], v[228:229]
	global_store_dwordx4 v157, v[122:125], s[76:77] offset:64 nt
	global_load_dwordx4 v[228:231], v157, s[74:75] offset:576 nt
	s_waitcnt vmcnt(7)
	v_pk_fma_f32 v[120:121], v[120:121], v[150:151], v[234:235]
	v_pk_fma_f32 v[118:119], v[118:119], v[148:149], v[232:233]
	global_store_dwordx4 v157, v[118:121], s[76:77] offset:512 nt
	s_add_u32 s74, s74, 0x20000
	s_addc_u32 s75, s75, 0
	global_load_dwordx4 v[232:235], v157, s[74:75] nt
	s_waitcnt vmcnt(8)
	v_pk_fma_f32 v[116:117], v[116:117], v[170:171], v[238:239]
	v_pk_fma_f32 v[114:115], v[114:115], v[168:169], v[236:237]
	global_store_dwordx4 v157, v[114:117], s[76:77] offset:576 nt
	global_load_dwordx4 v[236:239], v157, s[74:75] offset:64 nt
	s_add_u32 s76, s76, 0x20000
	s_addc_u32 s77, s77, 0
	s_waitcnt vmcnt(9)
	v_pk_fma_f32 v[112:113], v[112:113], v[142:143], v[242:243]
	v_pk_fma_f32 v[110:111], v[110:111], v[140:141], v[240:241]
	global_store_dwordx4 v157, v[110:113], s[76:77] nt
	global_load_dwordx4 v[240:243], v157, s[74:75] offset:512 nt
	s_waitcnt vmcnt(10)
	v_pk_fma_f32 v[108:109], v[108:109], v[146:147], v[246:247]
	v_pk_fma_f32 v[106:107], v[106:107], v[144:145], v[244:245]
	global_store_dwordx4 v157, v[106:109], s[76:77] offset:64 nt
	global_load_dwordx4 v[244:247], v157, s[74:75] offset:576 nt
	s_waitcnt vmcnt(10)
	v_pk_fma_f32 v[104:105], v[104:105], v[150:151], v[226:227]
	v_pk_fma_f32 v[102:103], v[102:103], v[148:149], v[224:225]
	global_store_dwordx4 v157, v[102:105], s[76:77] offset:512 nt
	s_add_u32 s74, s74, 0x20000
	s_addc_u32 s75, s75, 0
	global_load_dwordx4 v[224:227], v157, s[74:75] nt
	s_waitcnt vmcnt(10)
	v_pk_fma_f32 v[100:101], v[100:101], v[170:171], v[230:231]
	v_pk_fma_f32 v[98:99], v[98:99], v[168:169], v[228:229]
	global_store_dwordx4 v157, v[98:101], s[76:77] offset:576 nt
	global_load_dwordx4 v[228:231], v157, s[74:75] offset:64 nt
	s_add_u32 s76, s76, 0x20000
	s_addc_u32 s77, s77, 0
	s_waitcnt vmcnt(10)
	v_pk_fma_f32 v[96:97], v[96:97], v[142:143], v[234:235]
	v_pk_fma_f32 v[94:95], v[94:95], v[140:141], v[232:233]
	global_store_dwordx4 v157, v[94:97], s[76:77] nt
	global_load_dwordx4 v[232:235], v157, s[74:75] offset:512 nt
	s_waitcnt vmcnt(10)
	v_pk_fma_f32 v[92:93], v[92:93], v[146:147], v[238:239]
	v_pk_fma_f32 v[90:91], v[90:91], v[144:145], v[236:237]
	global_store_dwordx4 v157, v[90:93], s[76:77] offset:64 nt
	global_load_dwordx4 v[236:239], v157, s[74:75] offset:576 nt
	s_waitcnt vmcnt(10)
	v_pk_fma_f32 v[88:89], v[88:89], v[150:151], v[242:243]
	v_pk_fma_f32 v[86:87], v[86:87], v[148:149], v[240:241]
	global_store_dwordx4 v157, v[86:89], s[76:77] offset:512 nt
	s_add_u32 s74, s74, 0xa0000
	s_addc_u32 s75, s75, 0
	global_load_dwordx4 v[240:243], v157, s[74:75] nt
	s_waitcnt vmcnt(10)
	v_pk_fma_f32 v[84:85], v[84:85], v[170:171], v[246:247]
	v_pk_fma_f32 v[82:83], v[82:83], v[168:169], v[244:245]
	global_store_dwordx4 v157, v[82:85], s[76:77] offset:576 nt
	global_load_dwordx4 v[244:247], v157, s[74:75] offset:64 nt
	s_add_u32 s76, s76, 0x20000
	s_addc_u32 s77, s77, 0
	s_waitcnt vmcnt(10)
	v_pk_fma_f32 v[80:81], v[80:81], v[142:143], v[226:227]
	v_pk_fma_f32 v[78:79], v[78:79], v[140:141], v[224:225]
	global_store_dwordx4 v157, v[78:81], s[76:77] nt
	global_load_dwordx4 v[224:227], v157, s[74:75] offset:512 nt
	s_waitcnt vmcnt(10)
	v_pk_fma_f32 v[76:77], v[76:77], v[146:147], v[230:231]
	v_pk_fma_f32 v[74:75], v[74:75], v[144:145], v[228:229]
	global_store_dwordx4 v157, v[74:77], s[76:77] offset:64 nt
	global_load_dwordx4 v[228:231], v157, s[74:75] offset:576 nt
	s_waitcnt vmcnt(10)
	v_pk_fma_f32 v[72:73], v[72:73], v[150:151], v[234:235]
	v_pk_fma_f32 v[70:71], v[70:71], v[148:149], v[232:233]
	global_store_dwordx4 v157, v[70:73], s[76:77] offset:512 nt
	s_add_u32 s74, s74, 0x20000
	s_addc_u32 s75, s75, 0
	global_load_dwordx4 v[232:235], v157, s[74:75] nt
	s_waitcnt vmcnt(10)
	v_pk_fma_f32 v[68:69], v[68:69], v[170:171], v[238:239]
	v_pk_fma_f32 v[66:67], v[66:67], v[168:169], v[236:237]
	global_store_dwordx4 v157, v[66:69], s[76:77] offset:576 nt
	global_load_dwordx4 v[236:239], v157, s[74:75] offset:64 nt
	s_add_u32 s76, s76, 0xa0000
	s_addc_u32 s77, s77, 0
	s_waitcnt vmcnt(10)
	v_pk_fma_f32 v[64:65], v[64:65], v[142:143], v[242:243]
	v_pk_fma_f32 v[62:63], v[62:63], v[140:141], v[240:241]
	global_store_dwordx4 v157, v[62:65], s[76:77] nt
	global_load_dwordx4 v[240:243], v157, s[74:75] offset:512 nt
	s_waitcnt vmcnt(10)
	v_pk_fma_f32 v[60:61], v[60:61], v[146:147], v[246:247]
	v_pk_fma_f32 v[58:59], v[58:59], v[144:145], v[244:245]
	global_store_dwordx4 v157, v[58:61], s[76:77] offset:64 nt
	global_load_dwordx4 v[244:247], v157, s[74:75] offset:576 nt
	s_waitcnt vmcnt(10)
	v_pk_fma_f32 v[56:57], v[56:57], v[150:151], v[226:227]
	v_pk_fma_f32 v[54:55], v[54:55], v[148:149], v[224:225]
	global_store_dwordx4 v157, v[54:57], s[76:77] offset:512 nt
	s_add_u32 s74, s74, 0x20000
	s_addc_u32 s75, s75, 0
	global_load_dwordx4 v[224:227], v157, s[74:75] nt
	s_waitcnt vmcnt(10)
	v_pk_fma_f32 v[52:53], v[52:53], v[170:171], v[230:231]
	v_pk_fma_f32 v[50:51], v[50:51], v[168:169], v[228:229]
	global_store_dwordx4 v157, v[50:53], s[76:77] offset:576 nt
	global_load_dwordx4 v[228:231], v157, s[74:75] offset:64 nt
	s_add_u32 s76, s76, 0x20000
	s_addc_u32 s77, s77, 0
	s_waitcnt vmcnt(10)
	v_pk_fma_f32 v[48:49], v[48:49], v[142:143], v[234:235]
	v_pk_fma_f32 v[46:47], v[46:47], v[140:141], v[232:233]
	global_store_dwordx4 v157, v[46:49], s[76:77] nt
	global_load_dwordx4 v[232:235], v157, s[74:75] offset:512 nt
	s_waitcnt vmcnt(10)
	v_pk_fma_f32 v[44:45], v[44:45], v[146:147], v[238:239]
	v_pk_fma_f32 v[42:43], v[42:43], v[144:145], v[236:237]
	global_store_dwordx4 v157, v[42:45], s[76:77] offset:64 nt
	global_load_dwordx4 v[236:239], v157, s[74:75] offset:576 nt
	s_waitcnt vmcnt(10)
	v_pk_fma_f32 v[40:41], v[40:41], v[150:151], v[242:243]
	v_pk_fma_f32 v[38:39], v[38:39], v[148:149], v[240:241]
	global_store_dwordx4 v157, v[38:41], s[76:77] offset:512 nt
	s_add_u32 s74, s74, 0x20000
	s_addc_u32 s75, s75, 0
	global_load_dwordx4 v[240:243], v157, s[74:75] nt
	s_waitcnt vmcnt(10)
	v_pk_fma_f32 v[36:37], v[36:37], v[170:171], v[246:247]
	v_pk_fma_f32 v[34:35], v[34:35], v[168:169], v[244:245]
	global_store_dwordx4 v157, v[34:37], s[76:77] offset:576 nt
	global_load_dwordx4 v[244:247], v157, s[74:75] offset:64 nt
	s_add_u32 s76, s76, 0x20000
	s_addc_u32 s77, s77, 0
	s_waitcnt vmcnt(10)
	v_pk_fma_f32 v[32:33], v[32:33], v[142:143], v[226:227]
	v_pk_fma_f32 v[30:31], v[30:31], v[140:141], v[224:225]
	global_store_dwordx4 v157, v[30:33], s[76:77] nt
	global_load_dwordx4 v[224:227], v157, s[74:75] offset:512 nt
	s_waitcnt vmcnt(10)
	v_pk_fma_f32 v[28:29], v[28:29], v[146:147], v[230:231]
	v_pk_fma_f32 v[26:27], v[26:27], v[144:145], v[228:229]
	global_store_dwordx4 v157, v[26:29], s[76:77] offset:64 nt
	global_load_dwordx4 v[228:231], v157, s[74:75] offset:576 nt
	s_waitcnt vmcnt(10)
	v_pk_fma_f32 v[24:25], v[24:25], v[150:151], v[234:235]
	v_pk_fma_f32 v[22:23], v[22:23], v[148:149], v[232:233]
	global_store_dwordx4 v157, v[22:25], s[76:77] offset:512 nt
	s_waitcnt vmcnt(9)
	v_pk_fma_f32 v[20:21], v[20:21], v[170:171], v[238:239]
	v_pk_fma_f32 v[18:19], v[18:19], v[168:169], v[236:237]
	global_store_dwordx4 v157, v[18:21], s[76:77] offset:576 nt
	s_add_u32 s76, s76, 0x20000
	s_addc_u32 s77, s77, 0
	s_waitcnt vmcnt(8)
	v_pk_fma_f32 v[16:17], v[16:17], v[142:143], v[242:243]
	v_pk_fma_f32 v[14:15], v[14:15], v[140:141], v[240:241]
	global_store_dwordx4 v157, v[14:17], s[76:77] nt
	s_waitcnt vmcnt(7)
	v_pk_fma_f32 v[12:13], v[12:13], v[146:147], v[246:247]
	v_pk_fma_f32 v[10:11], v[10:11], v[144:145], v[244:245]
	global_store_dwordx4 v157, v[10:13], s[76:77] offset:64 nt
	s_waitcnt vmcnt(6)
	v_pk_fma_f32 v[8:9], v[8:9], v[150:151], v[226:227]
	v_pk_fma_f32 v[6:7], v[6:7], v[148:149], v[224:225]
	global_store_dwordx4 v157, v[6:9], s[76:77] offset:512 nt
	s_waitcnt vmcnt(5)
	v_pk_fma_f32 v[4:5], v[4:5], v[170:171], v[230:231]
	v_pk_fma_f32 v[2:3], v[2:3], v[168:169], v[228:229]
	global_store_dwordx4 v157, v[2:5], s[76:77] offset:576 nt
	s_branch .LBB0_24

.LBB0_234:
	s_add_u32 s39, s46, 0xfff80080
	s_addc_u32 s48, s47, -1
	s_add_i32 s62, 0, 0x10000
	ds_read_b128 v[144:147], v141
	ds_read_b128 v[148:151], v141 offset:1024
	ds_read_b128 v[152:155], v141 offset:2048
	ds_read_b128 v[168:171], v141 offset:3072
	s_cmp_eq_u32 s13, 28
	s_cselect_b32 s51, s43, s48
	s_cselect_b32 s50, s42, s39
	s_cselect_b32 s49, s45, s12
	s_cselect_b32 s48, s44, s1
	ds_read_b128 v[172:175], v143
	ds_read_b128 v[176:179], v143 offset:1024
	ds_read_b128 v[180:183], v143 offset:2048
	ds_read_b128 v[184:187], v143 offset:3072
	ds_read_b128 v[188:191], v143 offset:4096
	ds_read_b128 v[192:195], v143 offset:5120
	ds_read_b128 v[196:199], v143 offset:6144
	ds_read_b128 v[224:227], v143 offset:7168
	s_add_i32 m0, s53, 0xc000
	s_nop 0
	global_load_lds_dwordx4 v136, s[46:47]
	s_add_i32 m0, s53, 0xe000
	s_add_i32 s39, 0, 0x14000
	global_load_lds_dwordx4 v138, s[46:47]
	s_add_i32 s62, s62, s52
	ds_read_b128 v[228:231], v141 offset:16384
	ds_read_b128 v[232:235], v141 offset:17408
	ds_read_b128 v[236:239], v141 offset:18432
	ds_read_b128 v[240:243], v141 offset:19456
	s_waitcnt lgkmcnt(0)
	s_nop 0
	s_barrier
	v_mfma_f32_16x16x32_bf16 v[126:129], v[144:147], v[172:175], v[126:129]
	v_mfma_f32_16x16x32_bf16 v[122:125], v[152:155], v[172:175], v[122:125]
	v_mfma_f32_16x16x32_bf16 v[118:121], v[144:147], v[180:183], v[118:121]
	v_mfma_f32_16x16x32_bf16 v[114:117], v[152:155], v[180:183], v[114:117]
	v_mfma_f32_16x16x32_bf16 v[102:105], v[144:147], v[188:191], v[102:105]
	v_mfma_f32_16x16x32_bf16 v[98:101], v[152:155], v[188:191], v[98:101]
	v_mfma_f32_16x16x32_bf16 v[86:89], v[144:147], v[196:199], v[86:89]
	v_mfma_f32_16x16x32_bf16 v[82:85], v[152:155], v[196:199], v[82:85]
	v_mfma_f32_16x16x32_bf16 v[126:129], v[148:151], v[176:179], v[126:129]
	v_mfma_f32_16x16x32_bf16 v[122:125], v[168:171], v[176:179], v[122:125]
	v_mfma_f32_16x16x32_bf16 v[118:121], v[148:151], v[184:187], v[118:121]
	v_mfma_f32_16x16x32_bf16 v[114:117], v[168:171], v[184:187], v[114:117]
	v_mfma_f32_16x16x32_bf16 v[102:105], v[148:151], v[192:195], v[102:105]
	v_mfma_f32_16x16x32_bf16 v[98:101], v[168:171], v[192:195], v[98:101]
	v_mfma_f32_16x16x32_bf16 v[86:89], v[148:151], v[224:227], v[86:89]
	v_mfma_f32_16x16x32_bf16 v[82:85], v[168:171], v[224:227], v[82:85]
	v_mfma_f32_16x16x32_bf16 v[110:113], v[228:231], v[172:175], v[110:113]
	v_mfma_f32_16x16x32_bf16 v[106:109], v[236:239], v[172:175], v[106:109]
	v_mfma_f32_16x16x32_bf16 v[94:97], v[228:231], v[180:183], v[94:97]
	v_mfma_f32_16x16x32_bf16 v[90:93], v[236:239], v[180:183], v[90:93]
	v_mfma_f32_16x16x32_bf16 v[78:81], v[228:231], v[188:191], v[78:81]
	v_mfma_f32_16x16x32_bf16 v[74:77], v[236:239], v[188:191], v[74:77]
	v_mfma_f32_16x16x32_bf16 v[70:73], v[228:231], v[196:199], v[70:73]
	v_mfma_f32_16x16x32_bf16 v[66:69], v[236:239], v[196:199], v[66:69]
	v_mfma_f32_16x16x32_bf16 v[110:113], v[232:235], v[176:179], v[110:113]
	v_mfma_f32_16x16x32_bf16 v[106:109], v[240:243], v[176:179], v[106:109]
	v_mfma_f32_16x16x32_bf16 v[94:97], v[232:235], v[184:187], v[94:97]
	v_mfma_f32_16x16x32_bf16 v[90:93], v[240:243], v[184:187], v[90:93]
	v_mfma_f32_16x16x32_bf16 v[78:81], v[232:235], v[192:195], v[78:81]
	v_mfma_f32_16x16x32_bf16 v[74:77], v[240:243], v[192:195], v[74:77]
	v_mfma_f32_16x16x32_bf16 v[70:73], v[232:235], v[224:227], v[70:73]
	v_mfma_f32_16x16x32_bf16 v[66:69], v[240:243], v[224:227], v[66:69]
	s_barrier
	s_mov_b32 m0, s53
	s_add_u32 s78, s50, s94
	s_addc_u32 s79, s51, s95
	ds_read_b128 v[172:175], v143 offset:16384
	ds_read_b128 v[176:179], v143 offset:17408
	ds_read_b128 v[180:183], v143 offset:18432
	ds_read_b128 v[184:187], v143 offset:19456
	ds_read_b128 v[188:191], v143 offset:20480
	ds_read_b128 v[192:195], v143 offset:21504
	ds_read_b128 v[196:199], v143 offset:22528
	ds_read_b128 v[224:227], v143 offset:23552
	global_load_lds_dwordx4 v134, s[50:51]
	s_mov_b32 m0, s54
	s_add_u32 s76, s48, s94
	s_addc_u32 s77, s49, s95
	global_load_lds_dwordx4 v132, s[50:51]
	s_mov_b32 m0, s62
	s_nop 0
	global_load_lds_dwordx4 v0, s[48:49]
	s_add_i32 m0, s62, 0x2000
	s_add_u32 s62, s48, 0x80000
	s_addc_u32 s63, s49, 0
	global_load_lds_dwordx4 v130, s[48:49]
	s_add_i32 s39, s39, s52
	s_mov_b32 m0, s39
	s_nop 0
	global_load_lds_dwordx4 v0, s[62:63]
	s_add_i32 m0, s39, 0x2000
	s_nop 0
	global_load_lds_dwordx4 v130, s[62:63]
	s_waitcnt vmcnt(6) lgkmcnt(0)
	s_barrier
	v_mfma_f32_16x16x32_bf16 v[62:65], v[144:147], v[172:175], v[62:65]
	v_mfma_f32_16x16x32_bf16 v[58:61], v[152:155], v[172:175], v[58:61]
	v_mfma_f32_16x16x32_bf16 v[54:57], v[144:147], v[180:183], v[54:57]
	v_mfma_f32_16x16x32_bf16 v[50:53], v[152:155], v[180:183], v[50:53]
	v_mfma_f32_16x16x32_bf16 v[38:41], v[144:147], v[188:191], v[38:41]
	v_mfma_f32_16x16x32_bf16 v[34:37], v[152:155], v[188:191], v[34:37]
	v_mfma_f32_16x16x32_bf16 v[22:25], v[144:147], v[196:199], v[22:25]
	v_mfma_f32_16x16x32_bf16 v[18:21], v[152:155], v[196:199], v[18:21]
	v_mfma_f32_16x16x32_bf16 v[62:65], v[148:151], v[176:179], v[62:65]
	v_mfma_f32_16x16x32_bf16 v[58:61], v[168:171], v[176:179], v[58:61]
	v_mfma_f32_16x16x32_bf16 v[54:57], v[148:151], v[184:187], v[54:57]
	v_mfma_f32_16x16x32_bf16 v[50:53], v[168:171], v[184:187], v[50:53]
	v_mfma_f32_16x16x32_bf16 v[38:41], v[148:151], v[192:195], v[38:41]
	v_mfma_f32_16x16x32_bf16 v[34:37], v[168:171], v[192:195], v[34:37]
	v_mfma_f32_16x16x32_bf16 v[22:25], v[148:151], v[224:227], v[22:25]
	v_mfma_f32_16x16x32_bf16 v[18:21], v[168:171], v[224:227], v[18:21]
	v_mfma_f32_16x16x32_bf16 v[46:49], v[228:231], v[172:175], v[46:49]
	v_mfma_f32_16x16x32_bf16 v[42:45], v[236:239], v[172:175], v[42:45]
	v_mfma_f32_16x16x32_bf16 v[30:33], v[228:231], v[180:183], v[30:33]
	v_mfma_f32_16x16x32_bf16 v[26:29], v[236:239], v[180:183], v[26:29]
	v_mfma_f32_16x16x32_bf16 v[14:17], v[228:231], v[188:191], v[14:17]
	v_mfma_f32_16x16x32_bf16 v[10:13], v[236:239], v[188:191], v[10:13]
	v_mfma_f32_16x16x32_bf16 v[6:9], v[228:231], v[196:199], v[6:9]
	v_mfma_f32_16x16x32_bf16 v[2:5], v[236:239], v[196:199], v[2:5]
	v_mfma_f32_16x16x32_bf16 v[46:49], v[232:235], v[176:179], v[46:49]
	v_mfma_f32_16x16x32_bf16 v[42:45], v[240:243], v[176:179], v[42:45]
	v_mfma_f32_16x16x32_bf16 v[30:33], v[232:235], v[184:187], v[30:33]
	v_mfma_f32_16x16x32_bf16 v[26:29], v[240:243], v[184:187], v[26:29]
	v_mfma_f32_16x16x32_bf16 v[14:17], v[232:235], v[192:195], v[14:17]
	v_mfma_f32_16x16x32_bf16 v[10:13], v[240:243], v[192:195], v[10:13]
	v_mfma_f32_16x16x32_bf16 v[6:9], v[232:235], v[224:227], v[6:9]
	v_mfma_f32_16x16x32_bf16 v[2:5], v[240:243], v[224:227], v[2:5]
	s_barrier
	s_add_i32 s39, 0, 0x18000
	ds_read_b128 v[144:147], v141 offset:32768
	ds_read_b128 v[148:151], v141 offset:33792
	ds_read_b128 v[152:155], v141 offset:34816
	ds_read_b128 v[168:171], v141 offset:35840
	s_add_u32 s50, s50, 0x80000
	s_addc_u32 s51, s51, 0
	ds_read_b128 v[172:175], v143 offset:32768
	ds_read_b128 v[176:179], v143 offset:33792
	ds_read_b128 v[180:183], v143 offset:34816
	ds_read_b128 v[184:187], v143 offset:35840
	ds_read_b128 v[188:191], v143 offset:36864
	ds_read_b128 v[192:195], v143 offset:37888
	ds_read_b128 v[196:199], v143 offset:38912
	ds_read_b128 v[224:227], v143 offset:39936
	s_mov_b32 m0, s55
	s_nop 0
	global_load_lds_dwordx4 v134, s[50:51]
	s_mov_b32 m0, s56
	s_nop 0
	global_load_lds_dwordx4 v132, s[50:51]
	s_add_i32 s50, 0, 0x1c000
	s_add_i32 s39, s39, s52
	ds_read_b128 v[228:231], v141 offset:49152
	ds_read_b128 v[232:235], v141 offset:50176
	ds_read_b128 v[236:239], v141 offset:51200
	ds_read_b128 v[240:243], v141 offset:52224
	s_waitcnt lgkmcnt(0)
	s_nop 0
	s_barrier
	v_mfma_f32_16x16x32_bf16 v[126:129], v[144:147], v[172:175], v[126:129]
	v_mfma_f32_16x16x32_bf16 v[122:125], v[152:155], v[172:175], v[122:125]
	v_mfma_f32_16x16x32_bf16 v[118:121], v[144:147], v[180:183], v[118:121]
	v_mfma_f32_16x16x32_bf16 v[114:117], v[152:155], v[180:183], v[114:117]
	v_mfma_f32_16x16x32_bf16 v[102:105], v[144:147], v[188:191], v[102:105]
	v_mfma_f32_16x16x32_bf16 v[98:101], v[152:155], v[188:191], v[98:101]
	v_mfma_f32_16x16x32_bf16 v[86:89], v[144:147], v[196:199], v[86:89]
	v_mfma_f32_16x16x32_bf16 v[82:85], v[152:155], v[196:199], v[82:85]
	v_mfma_f32_16x16x32_bf16 v[126:129], v[148:151], v[176:179], v[126:129]
	v_mfma_f32_16x16x32_bf16 v[122:125], v[168:171], v[176:179], v[122:125]
	v_mfma_f32_16x16x32_bf16 v[118:121], v[148:151], v[184:187], v[118:121]
	v_mfma_f32_16x16x32_bf16 v[114:117], v[168:171], v[184:187], v[114:117]
	v_mfma_f32_16x16x32_bf16 v[102:105], v[148:151], v[192:195], v[102:105]
	v_mfma_f32_16x16x32_bf16 v[98:101], v[168:171], v[192:195], v[98:101]
	v_mfma_f32_16x16x32_bf16 v[86:89], v[148:151], v[224:227], v[86:89]
	v_mfma_f32_16x16x32_bf16 v[82:85], v[168:171], v[224:227], v[82:85]
	v_mfma_f32_16x16x32_bf16 v[110:113], v[228:231], v[172:175], v[110:113]
	v_mfma_f32_16x16x32_bf16 v[106:109], v[236:239], v[172:175], v[106:109]
	v_mfma_f32_16x16x32_bf16 v[94:97], v[228:231], v[180:183], v[94:97]
	v_mfma_f32_16x16x32_bf16 v[90:93], v[236:239], v[180:183], v[90:93]
	v_mfma_f32_16x16x32_bf16 v[78:81], v[228:231], v[188:191], v[78:81]
	v_mfma_f32_16x16x32_bf16 v[74:77], v[236:239], v[188:191], v[74:77]
	v_mfma_f32_16x16x32_bf16 v[70:73], v[228:231], v[196:199], v[70:73]
	v_mfma_f32_16x16x32_bf16 v[66:69], v[236:239], v[196:199], v[66:69]
	v_mfma_f32_16x16x32_bf16 v[110:113], v[232:235], v[176:179], v[110:113]
	v_mfma_f32_16x16x32_bf16 v[106:109], v[240:243], v[176:179], v[106:109]
	v_mfma_f32_16x16x32_bf16 v[94:97], v[232:235], v[184:187], v[94:97]
	v_mfma_f32_16x16x32_bf16 v[90:93], v[240:243], v[184:187], v[90:93]
	v_mfma_f32_16x16x32_bf16 v[78:81], v[232:235], v[192:195], v[78:81]
	v_mfma_f32_16x16x32_bf16 v[74:77], v[240:243], v[192:195], v[74:77]
	v_mfma_f32_16x16x32_bf16 v[70:73], v[232:235], v[224:227], v[70:73]
	v_mfma_f32_16x16x32_bf16 v[66:69], v[240:243], v[224:227], v[66:69]
	s_barrier
	s_mov_b32 m0, s57
	ds_read_b128 v[172:175], v143 offset:49152
	ds_read_b128 v[176:179], v143 offset:50176
	ds_read_b128 v[180:183], v143 offset:51200
	ds_read_b128 v[184:187], v143 offset:52224
	ds_read_b128 v[188:191], v143 offset:53248
	ds_read_b128 v[192:195], v143 offset:54272
	ds_read_b128 v[196:199], v143 offset:55296
	ds_read_b128 v[224:227], v143 offset:56320
	global_load_lds_dwordx4 v134, s[78:79]
	s_mov_b32 m0, s58
	s_nop 0
	global_load_lds_dwordx4 v132, s[78:79]
	s_mov_b32 m0, s39
	s_nop 0
	global_load_lds_dwordx4 v0, s[76:77]
	s_add_i32 m0, s39, 0x2000
	s_add_u32 s48, s48, 0x80080
	s_addc_u32 s49, s49, 0
	global_load_lds_dwordx4 v130, s[76:77]
	s_add_i32 s39, s50, s52
	s_mov_b32 m0, s39
	s_nop 0
	global_load_lds_dwordx4 v0, s[48:49]
	s_add_i32 m0, s39, 0x2000
	s_nop 0
	global_load_lds_dwordx4 v130, s[48:49]
	s_waitcnt vmcnt(6) lgkmcnt(0)
	s_nop 0
	s_barrier
	v_mfma_f32_16x16x32_bf16 v[62:65], v[144:147], v[172:175], v[62:65]
	v_mfma_f32_16x16x32_bf16 v[58:61], v[152:155], v[172:175], v[58:61]
	v_mfma_f32_16x16x32_bf16 v[54:57], v[144:147], v[180:183], v[54:57]
	v_mfma_f32_16x16x32_bf16 v[50:53], v[152:155], v[180:183], v[50:53]
	v_mfma_f32_16x16x32_bf16 v[38:41], v[144:147], v[188:191], v[38:41]
	v_mfma_f32_16x16x32_bf16 v[34:37], v[152:155], v[188:191], v[34:37]
	v_mfma_f32_16x16x32_bf16 v[22:25], v[144:147], v[196:199], v[22:25]
	v_mfma_f32_16x16x32_bf16 v[18:21], v[152:155], v[196:199], v[18:21]
	v_mfma_f32_16x16x32_bf16 v[62:65], v[148:151], v[176:179], v[62:65]
	v_mfma_f32_16x16x32_bf16 v[58:61], v[168:171], v[176:179], v[58:61]
	v_mfma_f32_16x16x32_bf16 v[54:57], v[148:151], v[184:187], v[54:57]
	v_mfma_f32_16x16x32_bf16 v[50:53], v[168:171], v[184:187], v[50:53]
	v_mfma_f32_16x16x32_bf16 v[38:41], v[148:151], v[192:195], v[38:41]
	v_mfma_f32_16x16x32_bf16 v[34:37], v[168:171], v[192:195], v[34:37]
	v_mfma_f32_16x16x32_bf16 v[22:25], v[148:151], v[224:227], v[22:25]
	v_mfma_f32_16x16x32_bf16 v[18:21], v[168:171], v[224:227], v[18:21]
	v_mfma_f32_16x16x32_bf16 v[46:49], v[228:231], v[172:175], v[46:49]
	v_mfma_f32_16x16x32_bf16 v[42:45], v[236:239], v[172:175], v[42:45]
	v_mfma_f32_16x16x32_bf16 v[30:33], v[228:231], v[180:183], v[30:33]
	v_mfma_f32_16x16x32_bf16 v[26:29], v[236:239], v[180:183], v[26:29]
	v_mfma_f32_16x16x32_bf16 v[14:17], v[228:231], v[188:191], v[14:17]
	v_mfma_f32_16x16x32_bf16 v[10:13], v[236:239], v[188:191], v[10:13]
	v_mfma_f32_16x16x32_bf16 v[6:9], v[228:231], v[196:199], v[6:9]
	v_mfma_f32_16x16x32_bf16 v[2:5], v[236:239], v[196:199], v[2:5]
	v_mfma_f32_16x16x32_bf16 v[46:49], v[232:235], v[176:179], v[46:49]
	v_mfma_f32_16x16x32_bf16 v[42:45], v[240:243], v[176:179], v[42:45]
	v_mfma_f32_16x16x32_bf16 v[30:33], v[232:235], v[184:187], v[30:33]
	v_mfma_f32_16x16x32_bf16 v[26:29], v[240:243], v[184:187], v[26:29]
	v_mfma_f32_16x16x32_bf16 v[14:17], v[232:235], v[192:195], v[14:17]
	v_mfma_f32_16x16x32_bf16 v[10:13], v[240:243], v[192:195], v[10:13]
	v_mfma_f32_16x16x32_bf16 v[6:9], v[232:235], v[224:227], v[6:9]
	v_mfma_f32_16x16x32_bf16 v[2:5], v[240:243], v[224:227], v[2:5]
	s_barrier
	s_add_i32 s13, s13, 2
	s_add_u32 s46, s46, 0x100
	s_addc_u32 s47, s47, 0
	s_add_u32 s1, s1, 0x100
	s_addc_u32 s12, s12, 0
	s_cmp_gt_u32 s13, 29
	s_cbranch_scc0 .LBB0_234
	v_readlane_b32 s6, v255, 23
	v_lshl_add_u32 v150, s61, 8, v140
	v_lshl_or_b32 v144, s60, 8, v142
	v_readlane_b32 s7, v255, 24
	v_ashrrev_i32_e32 v145, 31, v144
	s_movk_i32 s1, 0x5800
	v_mov_b64_e32 v[146:147], s[6:7]
	v_cvt_pk_bf16_f32 v70, v70, v71
	v_cvt_pk_bf16_f32 v71, v72, v73
	v_cvt_pk_bf16_f32 v72, v66, v67
	v_add_u32_e32 v66, 0x80, v150
	v_mad_i64_i32 v[148:149], s[12:13], v150, s1, v[146:147]
	v_lshlrev_b64 v[144:145], 1, v[144:145]
	v_cvt_pk_bf16_f32 v110, v110, v111
	v_cvt_pk_bf16_f32 v111, v112, v113
	v_cvt_pk_bf16_f32 v112, v106, v107
	v_or_b32_e32 v106, 16, v150
	v_mad_i64_i32 v[66:67], s[12:13], v66, s1, v[146:147]
	v_cvt_pk_bf16_f32 v46, v46, v47
	v_cvt_pk_bf16_f32 v47, v48, v49
	v_cvt_pk_bf16_f32 v48, v42, v43
	v_add_u32_e32 v42, 0x90, v150
	v_lshl_add_u64 v[148:149], v[148:149], 0, v[144:145]
	v_cvt_pk_bf16_f32 v113, v108, v109
	v_mad_i64_i32 v[106:107], s[12:13], v106, s1, v[146:147]
	v_cvt_pk_bf16_f32 v94, v94, v95
	v_cvt_pk_bf16_f32 v95, v96, v97
	v_cvt_pk_bf16_f32 v96, v90, v91
	v_or_b32_e32 v90, 32, v150
	v_lshl_add_u64 v[66:67], v[66:67], 0, v[144:145]
	v_cvt_pk_bf16_f32 v49, v44, v45
	v_mad_i64_i32 v[42:43], s[12:13], v42, s1, v[146:147]
	v_cvt_pk_bf16_f32 v30, v30, v31
	v_cvt_pk_bf16_f32 v31, v32, v33
	v_cvt_pk_bf16_f32 v32, v26, v27
	v_add_u32_e32 v26, 0xa0, v150
	global_store_dwordx4 v[148:149], v[110:113], off offset:256
	v_cvt_pk_bf16_f32 v97, v92, v93
	v_mad_i64_i32 v[90:91], s[12:13], v90, s1, v[146:147]
	v_lshl_add_u64 v[110:111], v[106:107], 0, v[144:145]
	v_cvt_pk_bf16_f32 v78, v78, v79
	v_cvt_pk_bf16_f32 v79, v80, v81
	v_cvt_pk_bf16_f32 v80, v74, v75
	v_or_b32_e32 v74, 48, v150
	global_store_dwordx4 v[66:67], v[46:49], off offset:256
	v_cvt_pk_bf16_f32 v33, v28, v29
	v_mad_i64_i32 v[26:27], s[12:13], v26, s1, v[146:147]
	v_lshl_add_u64 v[46:47], v[42:43], 0, v[144:145]
	v_cvt_pk_bf16_f32 v14, v14, v15
	v_cvt_pk_bf16_f32 v15, v16, v17
	v_cvt_pk_bf16_f32 v16, v10, v11
	v_add_u32_e32 v10, 0xb0, v150
	global_store_dwordx4 v[110:111], v[94:97], off offset:256
	v_cvt_pk_bf16_f32 v81, v76, v77
	v_mad_i64_i32 v[74:75], s[12:13], v74, s1, v[146:147]
	v_lshl_add_u64 v[94:95], v[90:91], 0, v[144:145]
	global_store_dwordx4 v[46:47], v[30:33], off offset:256
	v_cvt_pk_bf16_f32 v17, v12, v13
	v_mad_i64_i32 v[10:11], s[12:13], v10, s1, v[146:147]
	v_lshl_add_u64 v[30:31], v[26:27], 0, v[144:145]
	v_cvt_pk_bf16_f32 v126, v126, v127
	v_cvt_pk_bf16_f32 v127, v128, v129
	v_cvt_pk_bf16_f32 v128, v122, v123
	v_cvt_pk_bf16_f32 v129, v124, v125
	v_cvt_pk_bf16_f32 v106, v118, v119
	v_cvt_pk_bf16_f32 v107, v120, v121
	v_cvt_pk_bf16_f32 v108, v114, v115
	v_cvt_pk_bf16_f32 v109, v116, v117
	v_cvt_pk_bf16_f32 v90, v102, v103
	v_cvt_pk_bf16_f32 v91, v104, v105
	v_cvt_pk_bf16_f32 v92, v98, v99
	v_cvt_pk_bf16_f32 v93, v100, v101
	global_store_dwordx4 v[94:95], v[78:81], off offset:256
	v_cvt_pk_bf16_f32 v76, v82, v83
	v_cvt_pk_bf16_f32 v77, v84, v85
	v_lshl_add_u64 v[78:79], v[74:75], 0, v[144:145]
	v_cvt_pk_bf16_f32 v74, v86, v87
	v_cvt_pk_bf16_f32 v75, v88, v89
	v_cvt_pk_bf16_f32 v73, v68, v69
	v_cvt_pk_bf16_f32 v62, v62, v63
	v_cvt_pk_bf16_f32 v63, v64, v65
	v_cvt_pk_bf16_f32 v64, v58, v59
	v_cvt_pk_bf16_f32 v65, v60, v61
	v_cvt_pk_bf16_f32 v42, v54, v55
	v_cvt_pk_bf16_f32 v43, v56, v57
	v_cvt_pk_bf16_f32 v44, v50, v51
	v_cvt_pk_bf16_f32 v45, v52, v53
	v_cvt_pk_bf16_f32 v26, v38, v39
	v_cvt_pk_bf16_f32 v27, v40, v41
	v_cvt_pk_bf16_f32 v28, v34, v35
	v_cvt_pk_bf16_f32 v29, v36, v37
	global_store_dwordx4 v[30:31], v[14:17], off offset:256
	v_cvt_pk_bf16_f32 v12, v18, v19
	v_cvt_pk_bf16_f32 v13, v20, v21
	v_lshl_add_u64 v[14:15], v[10:11], 0, v[144:145]
	v_cvt_pk_bf16_f32 v10, v22, v23
	v_cvt_pk_bf16_f32 v11, v24, v25
	v_cvt_pk_bf16_f32 v6, v6, v7
	v_cvt_pk_bf16_f32 v7, v8, v9
	v_cvt_pk_bf16_f32 v8, v2, v3
	v_cvt_pk_bf16_f32 v9, v4, v5
	s_and_b64 vcc, exec, s[40:41]
	s_mov_b32 s60, s0
	s_mov_b32 s61, s38
	s_mov_b64 s[48:49], s[44:45]
	s_mov_b64 s[46:47], s[42:43]
	global_store_dwordx4 v[148:149], v[126:129], off
	global_store_dwordx4 v[110:111], v[106:109], off
	global_store_dwordx4 v[94:95], v[90:93], off
	global_store_dwordx4 v[78:79], v[74:77], off
	global_store_dwordx4 v[78:79], v[70:73], off offset:256
	global_store_dwordx4 v[66:67], v[62:65], off
	global_store_dwordx4 v[46:47], v[42:45], off
	global_store_dwordx4 v[30:31], v[26:29], off
	global_store_dwordx4 v[14:15], v[10:13], off
	global_store_dwordx4 v[14:15], v[6:9], off offset:256
	s_cbranch_vccz .LBB0_227
	s_waitcnt vmcnt(0)
	v_readlane_b32 s60, v255, 21
	s_cmpk_gt_u32 s36, 0xff
	s_mov_b32 s18, s60
	v_readlane_b32 s61, v255, 22
	s_cbranch_scc1 .LBB0_238
	s_barrier

.LBB0_282:
	s_add_i32 s67, s50, 2
	s_add_u32 s51, s0, 0xfff80080
	s_addc_u32 s52, s1, -1
	s_add_i32 s68, 0, 0x10000
	ds_read_b128 v[136:139], v153
	ds_read_b128 v[140:143], v153 offset:1024
	ds_read_b128 v[144:147], v153 offset:2048
	ds_read_b128 v[148:151], v153 offset:3072
	s_cmp_eq_u32 s12, s50
	s_cselect_b32 s50, s48, s13
	s_cselect_b32 s53, s47, s52
	s_cselect_b32 s52, s46, s51
	s_cselect_b32 s51, s49, s66
	ds_read_b128 v[168:171], v155
	ds_read_b128 v[172:175], v155 offset:1024
	ds_read_b128 v[176:179], v155 offset:2048
	ds_read_b128 v[180:183], v155 offset:3072
	ds_read_b128 v[184:187], v155 offset:4096
	ds_read_b128 v[188:191], v155 offset:5120
	ds_read_b128 v[192:195], v155 offset:6144
	ds_read_b128 v[196:199], v155 offset:7168
	s_add_i32 m0, s55, 0xc000
	s_nop 0
	global_load_lds_dwordx4 v132, s[0:1]
	s_add_i32 m0, s55, 0xe000
	s_add_i32 s70, 0, 0x14000
	global_load_lds_dwordx4 v134, s[0:1]
	s_add_i32 s68, s68, s54
	ds_read_b128 v[224:227], v153 offset:16384
	ds_read_b128 v[228:231], v153 offset:17408
	ds_read_b128 v[232:235], v153 offset:18432
	ds_read_b128 v[236:239], v153 offset:19456
	s_waitcnt lgkmcnt(0)
	s_barrier
	v_mfma_f32_16x16x32_bf16 v[126:129], v[136:139], v[168:171], v[126:129]
	v_mfma_f32_16x16x32_bf16 v[122:125], v[144:147], v[168:171], v[122:125]
	v_mfma_f32_16x16x32_bf16 v[110:113], v[136:139], v[176:179], v[110:113]
	v_mfma_f32_16x16x32_bf16 v[106:109], v[144:147], v[176:179], v[106:109]
	v_mfma_f32_16x16x32_bf16 v[94:97], v[136:139], v[184:187], v[94:97]
	v_mfma_f32_16x16x32_bf16 v[90:93], v[144:147], v[184:187], v[90:93]
	v_mfma_f32_16x16x32_bf16 v[78:81], v[136:139], v[192:195], v[78:81]
	v_mfma_f32_16x16x32_bf16 v[74:77], v[144:147], v[192:195], v[74:77]
	v_mfma_f32_16x16x32_bf16 v[126:129], v[140:143], v[172:175], v[126:129]
	v_mfma_f32_16x16x32_bf16 v[122:125], v[148:151], v[172:175], v[122:125]
	v_mfma_f32_16x16x32_bf16 v[110:113], v[140:143], v[180:183], v[110:113]
	v_mfma_f32_16x16x32_bf16 v[106:109], v[148:151], v[180:183], v[106:109]
	v_mfma_f32_16x16x32_bf16 v[94:97], v[140:143], v[188:191], v[94:97]
	v_mfma_f32_16x16x32_bf16 v[90:93], v[148:151], v[188:191], v[90:93]
	v_mfma_f32_16x16x32_bf16 v[78:81], v[140:143], v[196:199], v[78:81]
	v_mfma_f32_16x16x32_bf16 v[74:77], v[148:151], v[196:199], v[74:77]
	v_mfma_f32_16x16x32_bf16 v[118:121], v[224:227], v[168:171], v[118:121]
	v_mfma_f32_16x16x32_bf16 v[114:117], v[232:235], v[168:171], v[114:117]
	v_mfma_f32_16x16x32_bf16 v[102:105], v[224:227], v[176:179], v[102:105]
	v_mfma_f32_16x16x32_bf16 v[98:101], v[232:235], v[176:179], v[98:101]
	v_mfma_f32_16x16x32_bf16 v[86:89], v[224:227], v[184:187], v[86:89]
	v_mfma_f32_16x16x32_bf16 v[82:85], v[232:235], v[184:187], v[82:85]
	v_mfma_f32_16x16x32_bf16 v[70:73], v[224:227], v[192:195], v[70:73]
	v_mfma_f32_16x16x32_bf16 v[66:69], v[232:235], v[192:195], v[66:69]
	v_mfma_f32_16x16x32_bf16 v[118:121], v[228:231], v[172:175], v[118:121]
	v_mfma_f32_16x16x32_bf16 v[114:117], v[236:239], v[172:175], v[114:117]
	v_mfma_f32_16x16x32_bf16 v[102:105], v[228:231], v[180:183], v[102:105]
	v_mfma_f32_16x16x32_bf16 v[98:101], v[236:239], v[180:183], v[98:101]
	v_mfma_f32_16x16x32_bf16 v[86:89], v[228:231], v[188:191], v[86:89]
	v_mfma_f32_16x16x32_bf16 v[82:85], v[236:239], v[188:191], v[82:85]
	v_mfma_f32_16x16x32_bf16 v[70:73], v[228:231], v[196:199], v[70:73]
	v_mfma_f32_16x16x32_bf16 v[66:69], v[236:239], v[196:199], v[66:69]
	s_barrier
	s_mov_b32 m0, s55
	s_add_u32 s78, s52, s94
	s_addc_u32 s79, s53, s95
	ds_read_b128 v[168:171], v155 offset:16384
	ds_read_b128 v[172:175], v155 offset:17408
	ds_read_b128 v[176:179], v155 offset:18432
	ds_read_b128 v[180:183], v155 offset:19456
	ds_read_b128 v[184:187], v155 offset:20480
	ds_read_b128 v[188:191], v155 offset:21504
	ds_read_b128 v[192:195], v155 offset:22528
	ds_read_b128 v[196:199], v155 offset:23552
	global_load_lds_dwordx4 v0, s[52:53]
	s_mov_b32 m0, s56
	s_add_u32 s76, s50, s94
	s_addc_u32 s77, s51, s95
	global_load_lds_dwordx4 v130, s[52:53]
	s_mov_b32 m0, s68
	s_nop 0
	global_load_lds_dwordx4 v0, s[50:51]
	s_add_i32 m0, s68, 0x2000
	s_add_u32 s68, s50, 0x80000
	s_addc_u32 s69, s51, 0
	global_load_lds_dwordx4 v130, s[50:51]
	s_add_i32 s70, s70, s54
	s_mov_b32 m0, s70
	s_nop 0
	global_load_lds_dwordx4 v0, s[68:69]
	s_add_i32 m0, s70, 0x2000
	s_nop 0
	global_load_lds_dwordx4 v130, s[68:69]
	s_waitcnt vmcnt(6) lgkmcnt(0)
	s_barrier
	v_mfma_f32_16x16x32_bf16 v[62:65], v[136:139], v[168:171], v[62:65]
	v_mfma_f32_16x16x32_bf16 v[58:61], v[144:147], v[168:171], v[58:61]
	v_mfma_f32_16x16x32_bf16 v[46:49], v[136:139], v[176:179], v[46:49]
	v_mfma_f32_16x16x32_bf16 v[42:45], v[144:147], v[176:179], v[42:45]
	v_mfma_f32_16x16x32_bf16 v[30:33], v[136:139], v[184:187], v[30:33]
	v_mfma_f32_16x16x32_bf16 v[26:29], v[144:147], v[184:187], v[26:29]
	v_mfma_f32_16x16x32_bf16 v[14:17], v[136:139], v[192:195], v[14:17]
	v_mfma_f32_16x16x32_bf16 v[10:13], v[144:147], v[192:195], v[10:13]
	v_mfma_f32_16x16x32_bf16 v[62:65], v[140:143], v[172:175], v[62:65]
	v_mfma_f32_16x16x32_bf16 v[58:61], v[148:151], v[172:175], v[58:61]
	v_mfma_f32_16x16x32_bf16 v[46:49], v[140:143], v[180:183], v[46:49]
	v_mfma_f32_16x16x32_bf16 v[42:45], v[148:151], v[180:183], v[42:45]
	v_mfma_f32_16x16x32_bf16 v[30:33], v[140:143], v[188:191], v[30:33]
	v_mfma_f32_16x16x32_bf16 v[26:29], v[148:151], v[188:191], v[26:29]
	v_mfma_f32_16x16x32_bf16 v[14:17], v[140:143], v[196:199], v[14:17]
	v_mfma_f32_16x16x32_bf16 v[10:13], v[148:151], v[196:199], v[10:13]
	v_mfma_f32_16x16x32_bf16 v[54:57], v[224:227], v[168:171], v[54:57]
	v_mfma_f32_16x16x32_bf16 v[50:53], v[232:235], v[168:171], v[50:53]
	v_mfma_f32_16x16x32_bf16 v[38:41], v[224:227], v[176:179], v[38:41]
	v_mfma_f32_16x16x32_bf16 v[34:37], v[232:235], v[176:179], v[34:37]
	v_mfma_f32_16x16x32_bf16 v[22:25], v[224:227], v[184:187], v[22:25]
	v_mfma_f32_16x16x32_bf16 v[18:21], v[232:235], v[184:187], v[18:21]
	v_mfma_f32_16x16x32_bf16 v[6:9], v[224:227], v[192:195], v[6:9]
	v_mfma_f32_16x16x32_bf16 v[2:5], v[232:235], v[192:195], v[2:5]
	v_mfma_f32_16x16x32_bf16 v[54:57], v[228:231], v[172:175], v[54:57]
	v_mfma_f32_16x16x32_bf16 v[50:53], v[236:239], v[172:175], v[50:53]
	v_mfma_f32_16x16x32_bf16 v[38:41], v[228:231], v[180:183], v[38:41]
	v_mfma_f32_16x16x32_bf16 v[34:37], v[236:239], v[180:183], v[34:37]
	v_mfma_f32_16x16x32_bf16 v[22:25], v[228:231], v[188:191], v[22:25]
	v_mfma_f32_16x16x32_bf16 v[18:21], v[236:239], v[188:191], v[18:21]
	v_mfma_f32_16x16x32_bf16 v[6:9], v[228:231], v[196:199], v[6:9]
	v_mfma_f32_16x16x32_bf16 v[2:5], v[236:239], v[196:199], v[2:5]
	s_barrier
	s_add_i32 s68, 0, 0x18000
	ds_read_b128 v[136:139], v153 offset:32768
	ds_read_b128 v[140:143], v153 offset:33792
	ds_read_b128 v[144:147], v153 offset:34816
	ds_read_b128 v[148:151], v153 offset:35840
	s_add_u32 s52, s52, 0x80000
	s_addc_u32 s53, s53, 0
	ds_read_b128 v[168:171], v155 offset:32768
	ds_read_b128 v[172:175], v155 offset:33792
	ds_read_b128 v[176:179], v155 offset:34816
	ds_read_b128 v[180:183], v155 offset:35840
	ds_read_b128 v[184:187], v155 offset:36864
	ds_read_b128 v[188:191], v155 offset:37888
	ds_read_b128 v[192:195], v155 offset:38912
	ds_read_b128 v[196:199], v155 offset:39936
	s_mov_b32 m0, s57
	s_nop 0
	global_load_lds_dwordx4 v0, s[52:53]
	s_mov_b32 m0, s58
	s_nop 0
	global_load_lds_dwordx4 v130, s[52:53]
	s_add_i32 s52, 0, 0x1c000
	s_add_i32 s53, s68, s54
	ds_read_b128 v[224:227], v153 offset:49152
	ds_read_b128 v[228:231], v153 offset:50176
	ds_read_b128 v[232:235], v153 offset:51200
	ds_read_b128 v[236:239], v153 offset:52224
	s_waitcnt lgkmcnt(0)
	s_nop 0
	s_barrier
	v_mfma_f32_16x16x32_bf16 v[126:129], v[136:139], v[168:171], v[126:129]
	v_mfma_f32_16x16x32_bf16 v[122:125], v[144:147], v[168:171], v[122:125]
	v_mfma_f32_16x16x32_bf16 v[110:113], v[136:139], v[176:179], v[110:113]
	v_mfma_f32_16x16x32_bf16 v[106:109], v[144:147], v[176:179], v[106:109]
	v_mfma_f32_16x16x32_bf16 v[94:97], v[136:139], v[184:187], v[94:97]
	v_mfma_f32_16x16x32_bf16 v[90:93], v[144:147], v[184:187], v[90:93]
	v_mfma_f32_16x16x32_bf16 v[78:81], v[136:139], v[192:195], v[78:81]
	v_mfma_f32_16x16x32_bf16 v[74:77], v[144:147], v[192:195], v[74:77]
	v_mfma_f32_16x16x32_bf16 v[126:129], v[140:143], v[172:175], v[126:129]
	v_mfma_f32_16x16x32_bf16 v[122:125], v[148:151], v[172:175], v[122:125]
	v_mfma_f32_16x16x32_bf16 v[110:113], v[140:143], v[180:183], v[110:113]
	v_mfma_f32_16x16x32_bf16 v[106:109], v[148:151], v[180:183], v[106:109]
	v_mfma_f32_16x16x32_bf16 v[94:97], v[140:143], v[188:191], v[94:97]
	v_mfma_f32_16x16x32_bf16 v[90:93], v[148:151], v[188:191], v[90:93]
	v_mfma_f32_16x16x32_bf16 v[78:81], v[140:143], v[196:199], v[78:81]
	v_mfma_f32_16x16x32_bf16 v[74:77], v[148:151], v[196:199], v[74:77]
	v_mfma_f32_16x16x32_bf16 v[118:121], v[224:227], v[168:171], v[118:121]
	v_mfma_f32_16x16x32_bf16 v[114:117], v[232:235], v[168:171], v[114:117]
	v_mfma_f32_16x16x32_bf16 v[102:105], v[224:227], v[176:179], v[102:105]
	v_mfma_f32_16x16x32_bf16 v[98:101], v[232:235], v[176:179], v[98:101]
	v_mfma_f32_16x16x32_bf16 v[86:89], v[224:227], v[184:187], v[86:89]
	v_mfma_f32_16x16x32_bf16 v[82:85], v[232:235], v[184:187], v[82:85]
	v_mfma_f32_16x16x32_bf16 v[70:73], v[224:227], v[192:195], v[70:73]
	v_mfma_f32_16x16x32_bf16 v[66:69], v[232:235], v[192:195], v[66:69]
	v_mfma_f32_16x16x32_bf16 v[118:121], v[228:231], v[172:175], v[118:121]
	v_mfma_f32_16x16x32_bf16 v[114:117], v[236:239], v[172:175], v[114:117]
	v_mfma_f32_16x16x32_bf16 v[102:105], v[228:231], v[180:183], v[102:105]
	v_mfma_f32_16x16x32_bf16 v[98:101], v[236:239], v[180:183], v[98:101]
	v_mfma_f32_16x16x32_bf16 v[86:89], v[228:231], v[188:191], v[86:89]
	v_mfma_f32_16x16x32_bf16 v[82:85], v[236:239], v[188:191], v[82:85]
	v_mfma_f32_16x16x32_bf16 v[70:73], v[228:231], v[196:199], v[70:73]
	v_mfma_f32_16x16x32_bf16 v[66:69], v[236:239], v[196:199], v[66:69]
	s_barrier
	s_mov_b32 m0, s59
	ds_read_b128 v[168:171], v155 offset:49152
	ds_read_b128 v[172:175], v155 offset:50176
	ds_read_b128 v[176:179], v155 offset:51200
	ds_read_b128 v[180:183], v155 offset:52224
	ds_read_b128 v[184:187], v155 offset:53248
	ds_read_b128 v[188:191], v155 offset:54272
	ds_read_b128 v[192:195], v155 offset:55296
	ds_read_b128 v[196:199], v155 offset:56320
	global_load_lds_dwordx4 v0, s[78:79]
	s_mov_b32 m0, s60
	s_nop 0
	global_load_lds_dwordx4 v130, s[78:79]
	s_mov_b32 m0, s53
	s_nop 0
	global_load_lds_dwordx4 v0, s[76:77]
	s_add_i32 m0, s53, 0x2000
	s_add_u32 s50, s50, 0x80080
	s_addc_u32 s51, s51, 0
	global_load_lds_dwordx4 v130, s[76:77]
	s_add_i32 s52, s52, s54
	s_mov_b32 m0, s52
	s_nop 0
	global_load_lds_dwordx4 v0, s[50:51]
	s_add_i32 m0, s52, 0x2000
	s_nop 0
	global_load_lds_dwordx4 v130, s[50:51]
	s_waitcnt vmcnt(6) lgkmcnt(0)
	s_nop 0
	s_barrier
	v_mfma_f32_16x16x32_bf16 v[62:65], v[136:139], v[168:171], v[62:65]
	v_mfma_f32_16x16x32_bf16 v[58:61], v[144:147], v[168:171], v[58:61]
	v_mfma_f32_16x16x32_bf16 v[46:49], v[136:139], v[176:179], v[46:49]
	v_mfma_f32_16x16x32_bf16 v[42:45], v[144:147], v[176:179], v[42:45]
	v_mfma_f32_16x16x32_bf16 v[30:33], v[136:139], v[184:187], v[30:33]
	v_mfma_f32_16x16x32_bf16 v[26:29], v[144:147], v[184:187], v[26:29]
	v_mfma_f32_16x16x32_bf16 v[14:17], v[136:139], v[192:195], v[14:17]
	v_mfma_f32_16x16x32_bf16 v[10:13], v[144:147], v[192:195], v[10:13]
	v_mfma_f32_16x16x32_bf16 v[62:65], v[140:143], v[172:175], v[62:65]
	v_mfma_f32_16x16x32_bf16 v[58:61], v[148:151], v[172:175], v[58:61]
	v_mfma_f32_16x16x32_bf16 v[46:49], v[140:143], v[180:183], v[46:49]
	v_mfma_f32_16x16x32_bf16 v[42:45], v[148:151], v[180:183], v[42:45]
	v_mfma_f32_16x16x32_bf16 v[30:33], v[140:143], v[188:191], v[30:33]
	v_mfma_f32_16x16x32_bf16 v[26:29], v[148:151], v[188:191], v[26:29]
	v_mfma_f32_16x16x32_bf16 v[14:17], v[140:143], v[196:199], v[14:17]
	v_mfma_f32_16x16x32_bf16 v[10:13], v[148:151], v[196:199], v[10:13]
	v_mfma_f32_16x16x32_bf16 v[54:57], v[224:227], v[168:171], v[54:57]
	v_mfma_f32_16x16x32_bf16 v[50:53], v[232:235], v[168:171], v[50:53]
	v_mfma_f32_16x16x32_bf16 v[38:41], v[224:227], v[176:179], v[38:41]
	v_mfma_f32_16x16x32_bf16 v[34:37], v[232:235], v[176:179], v[34:37]
	v_mfma_f32_16x16x32_bf16 v[22:25], v[224:227], v[184:187], v[22:25]
	v_mfma_f32_16x16x32_bf16 v[18:21], v[232:235], v[184:187], v[18:21]
	v_mfma_f32_16x16x32_bf16 v[6:9], v[224:227], v[192:195], v[6:9]
	v_mfma_f32_16x16x32_bf16 v[2:5], v[232:235], v[192:195], v[2:5]
	v_mfma_f32_16x16x32_bf16 v[54:57], v[228:231], v[172:175], v[54:57]
	v_mfma_f32_16x16x32_bf16 v[50:53], v[236:239], v[172:175], v[50:53]
	v_mfma_f32_16x16x32_bf16 v[38:41], v[228:231], v[180:183], v[38:41]
	v_mfma_f32_16x16x32_bf16 v[34:37], v[236:239], v[180:183], v[34:37]
	v_mfma_f32_16x16x32_bf16 v[22:25], v[228:231], v[188:191], v[22:25]
	v_mfma_f32_16x16x32_bf16 v[18:21], v[236:239], v[188:191], v[18:21]
	v_mfma_f32_16x16x32_bf16 v[6:9], v[228:231], v[196:199], v[6:9]
	v_mfma_f32_16x16x32_bf16 v[2:5], v[236:239], v[196:199], v[2:5]
	s_barrier
	s_add_u32 s0, s0, 0x100
	s_addc_u32 s1, s1, 0
	s_add_u32 s13, s13, 0x100
	s_addc_u32 s66, s66, 0
	s_mov_b32 s50, s67
	s_cmp_ge_i32 s67, s41
	s_cbranch_scc0 .LBB0_282
	s_cmp_eq_u32 s63, 2
	s_cbranch_scc1 .Lepi6_orig
	v_readlane_b32 s90, v255, 17
	v_readlane_b32 s91, v255, 18
	v_readlane_b32 s96, v255, 19
	v_readlane_b32 s97, v255, 20
	v_readlane_b32 s8, v255, 25
	v_readlane_b32 s9, v255, 26
	v_readlane_b32 s68, v253, 58
	v_readlane_b32 s69, v253, 59
	v_lshl_or_b32 v156, s64, 8, v154
	v_lshlrev_b32_e32 v156, 2, v156
	v_lshl_add_u32 v157, v152, 13, v156
	s_lshl_b32 s72, s65, 21
	s_add_u32 s74, s68, s72
	s_addc_u32 s75, s69, 0
	s_add_u32 s76, s22, s72
	s_addc_u32 s77, s23, 0
	s_lshr_b32 s73, s65, 3
	s_mul_i32 s73, s73, 0xc000
	s_add_u32 s73, s73, 0x4000
	s_add_u32 s70, s90, s73
	s_addc_u32 s71, s91, 0
	global_load_dwordx4 v[140:143], v156, s[70:71]
	global_load_dwordx4 v[144:147], v156, s[70:71] offset:64
	global_load_dwordx4 v[148:151], v156, s[70:71] offset:512
	global_load_dwordx4 v[168:171], v156, s[70:71] offset:576
	global_load_dwordx4 v[224:227], v157, s[74:75] nt
	global_load_dwordx4 v[228:231], v157, s[74:75] offset:64 nt
	global_load_dwordx4 v[232:235], v157, s[74:75] offset:512 nt
	global_load_dwordx4 v[236:239], v157, s[74:75] offset:576 nt
	s_add_u32 s74, s74, 0x20000
	s_addc_u32 s75, s75, 0
	global_load_dwordx4 v[240:243], v157, s[74:75] nt
	global_load_dwordx4 v[244:247], v157, s[74:75] offset:64 nt
	s_waitcnt vmcnt(5)
	v_pk_fma_f32 v[128:129], v[128:129], v[142:143], v[226:227]
	v_pk_fma_f32 v[126:127], v[126:127], v[140:141], v[224:225]
	global_store_dwordx4 v157, v[126:129], s[76:77]
	global_load_dwordx4 v[224:227], v157, s[74:75] offset:512 nt
	s_waitcnt vmcnt(6)
	v_pk_fma_f32 v[124:125], v[124:125], v[146:147], v[230:231]
	v_pk_fma_f32 v[122:123], v[122:123], v[144:145], v[228:229]
	global_store_dwordx4 v157, v[122:125], s[76:77] offset:64
	global_load_dwordx4 v[228:231], v157, s[74:75] offset:576 nt
	s_waitcnt vmcnt(7)
	v_pk_fma_f32 v[120:121], v[120:121], v[150:151], v[234:235]
	v_pk_fma_f32 v[118:119], v[118:119], v[148:149], v[232:233]
	global_store_dwordx4 v157, v[118:121], s[76:77] offset:512
	s_add_u32 s74, s74, 0x20000
	s_addc_u32 s75, s75, 0
	global_load_dwordx4 v[232:235], v157, s[74:75] nt
	s_waitcnt vmcnt(8)
	v_pk_fma_f32 v[116:117], v[116:117], v[170:171], v[238:239]
	v_pk_fma_f32 v[114:115], v[114:115], v[168:169], v[236:237]
	global_store_dwordx4 v157, v[114:117], s[76:77] offset:576
	global_load_dwordx4 v[236:239], v157, s[74:75] offset:64 nt
	s_add_u32 s76, s76, 0x20000
	s_addc_u32 s77, s77, 0
	s_waitcnt vmcnt(9)
	v_pk_fma_f32 v[112:113], v[112:113], v[142:143], v[242:243]
	v_pk_fma_f32 v[110:111], v[110:111], v[140:141], v[240:241]
	global_store_dwordx4 v157, v[110:113], s[76:77]
	global_load_dwordx4 v[240:243], v157, s[74:75] offset:512 nt
	s_waitcnt vmcnt(10)
	v_pk_fma_f32 v[108:109], v[108:109], v[146:147], v[246:247]
	v_pk_fma_f32 v[106:107], v[106:107], v[144:145], v[244:245]
	global_store_dwordx4 v157, v[106:109], s[76:77] offset:64
	global_load_dwordx4 v[244:247], v157, s[74:75] offset:576 nt
	s_waitcnt vmcnt(10)
	v_pk_fma_f32 v[104:105], v[104:105], v[150:151], v[226:227]
	v_pk_fma_f32 v[102:103], v[102:103], v[148:149], v[224:225]
	global_store_dwordx4 v157, v[102:105], s[76:77] offset:512
	s_add_u32 s74, s74, 0x20000
	s_addc_u32 s75, s75, 0
	global_load_dwordx4 v[224:227], v157, s[74:75] nt
	s_waitcnt vmcnt(10)
	v_pk_fma_f32 v[100:101], v[100:101], v[170:171], v[230:231]
	v_pk_fma_f32 v[98:99], v[98:99], v[168:169], v[228:229]
	global_store_dwordx4 v157, v[98:101], s[76:77] offset:576
	global_load_dwordx4 v[228:231], v157, s[74:75] offset:64 nt
	s_add_u32 s76, s76, 0x20000
	s_addc_u32 s77, s77, 0
	s_waitcnt vmcnt(10)
	v_pk_fma_f32 v[96:97], v[96:97], v[142:143], v[234:235]
	v_pk_fma_f32 v[94:95], v[94:95], v[140:141], v[232:233]
	global_store_dwordx4 v157, v[94:97], s[76:77]
	global_load_dwordx4 v[232:235], v157, s[74:75] offset:512 nt
	s_waitcnt vmcnt(10)
	v_pk_fma_f32 v[92:93], v[92:93], v[146:147], v[238:239]
	v_pk_fma_f32 v[90:91], v[90:91], v[144:145], v[236:237]
	global_store_dwordx4 v157, v[90:93], s[76:77] offset:64
	global_load_dwordx4 v[236:239], v157, s[74:75] offset:576 nt
	s_waitcnt vmcnt(10)
	v_pk_fma_f32 v[88:89], v[88:89], v[150:151], v[242:243]
	v_pk_fma_f32 v[86:87], v[86:87], v[148:149], v[240:241]
	global_store_dwordx4 v157, v[86:89], s[76:77] offset:512
	s_add_u32 s74, s74, 0xa0000
	s_addc_u32 s75, s75, 0
	global_load_dwordx4 v[240:243], v157, s[74:75] nt
	s_waitcnt vmcnt(10)
	v_pk_fma_f32 v[84:85], v[84:85], v[170:171], v[246:247]
	v_pk_fma_f32 v[82:83], v[82:83], v[168:169], v[244:245]
	global_store_dwordx4 v157, v[82:85], s[76:77] offset:576
	global_load_dwordx4 v[244:247], v157, s[74:75] offset:64 nt
	s_add_u32 s76, s76, 0x20000
	s_addc_u32 s77, s77, 0
	s_waitcnt vmcnt(10)
	v_pk_fma_f32 v[80:81], v[80:81], v[142:143], v[226:227]
	v_pk_fma_f32 v[78:79], v[78:79], v[140:141], v[224:225]
	global_store_dwordx4 v157, v[78:81], s[76:77]
	global_load_dwordx4 v[224:227], v157, s[74:75] offset:512 nt
	s_waitcnt vmcnt(10)
	v_pk_fma_f32 v[76:77], v[76:77], v[146:147], v[230:231]
	v_pk_fma_f32 v[74:75], v[74:75], v[144:145], v[228:229]
	global_store_dwordx4 v157, v[74:77], s[76:77] offset:64
	global_load_dwordx4 v[228:231], v157, s[74:75] offset:576 nt
	s_waitcnt vmcnt(10)
	v_pk_fma_f32 v[72:73], v[72:73], v[150:151], v[234:235]
	v_pk_fma_f32 v[70:71], v[70:71], v[148:149], v[232:233]
	global_store_dwordx4 v157, v[70:73], s[76:77] offset:512
	s_add_u32 s74, s74, 0x20000
	s_addc_u32 s75, s75, 0
	global_load_dwordx4 v[232:235], v157, s[74:75] nt
	s_waitcnt vmcnt(10)
	v_pk_fma_f32 v[68:69], v[68:69], v[170:171], v[238:239]
	v_pk_fma_f32 v[66:67], v[66:67], v[168:169], v[236:237]
	global_store_dwordx4 v157, v[66:69], s[76:77] offset:576
	global_load_dwordx4 v[236:239], v157, s[74:75] offset:64 nt
	s_add_u32 s76, s76, 0xa0000
	s_addc_u32 s77, s77, 0
	s_waitcnt vmcnt(10)
	v_pk_fma_f32 v[64:65], v[64:65], v[142:143], v[242:243]
	v_pk_fma_f32 v[62:63], v[62:63], v[140:141], v[240:241]
	global_store_dwordx4 v157, v[62:65], s[76:77]
	global_load_dwordx4 v[240:243], v157, s[74:75] offset:512 nt
	s_waitcnt vmcnt(10)
	v_pk_fma_f32 v[60:61], v[60:61], v[146:147], v[246:247]
	v_pk_fma_f32 v[58:59], v[58:59], v[144:145], v[244:245]
	global_store_dwordx4 v157, v[58:61], s[76:77] offset:64
	global_load_dwordx4 v[244:247], v157, s[74:75] offset:576 nt
	s_waitcnt vmcnt(10)
	v_pk_fma_f32 v[56:57], v[56:57], v[150:151], v[226:227]
	v_pk_fma_f32 v[54:55], v[54:55], v[148:149], v[224:225]
	global_store_dwordx4 v157, v[54:57], s[76:77] offset:512
	s_add_u32 s74, s74, 0x20000
	s_addc_u32 s75, s75, 0
	global_load_dwordx4 v[224:227], v157, s[74:75] nt
	s_waitcnt vmcnt(10)
	v_pk_fma_f32 v[52:53], v[52:53], v[170:171], v[230:231]
	v_pk_fma_f32 v[50:51], v[50:51], v[168:169], v[228:229]
	global_store_dwordx4 v157, v[50:53], s[76:77] offset:576
	global_load_dwordx4 v[228:231], v157, s[74:75] offset:64 nt
	s_add_u32 s76, s76, 0x20000
	s_addc_u32 s77, s77, 0
	s_waitcnt vmcnt(10)
	v_pk_fma_f32 v[48:49], v[48:49], v[142:143], v[234:235]
	v_pk_fma_f32 v[46:47], v[46:47], v[140:141], v[232:233]
	global_store_dwordx4 v157, v[46:49], s[76:77]
	global_load_dwordx4 v[232:235], v157, s[74:75] offset:512 nt
	s_waitcnt vmcnt(10)
	v_pk_fma_f32 v[44:45], v[44:45], v[146:147], v[238:239]
	v_pk_fma_f32 v[42:43], v[42:43], v[144:145], v[236:237]
	global_store_dwordx4 v157, v[42:45], s[76:77] offset:64
	global_load_dwordx4 v[236:239], v157, s[74:75] offset:576 nt
	s_waitcnt vmcnt(10)
	v_pk_fma_f32 v[40:41], v[40:41], v[150:151], v[242:243]
	v_pk_fma_f32 v[38:39], v[38:39], v[148:149], v[240:241]
	global_store_dwordx4 v157, v[38:41], s[76:77] offset:512
	s_add_u32 s74, s74, 0x20000
	s_addc_u32 s75, s75, 0
	global_load_dwordx4 v[240:243], v157, s[74:75] nt
	s_waitcnt vmcnt(10)
	v_pk_fma_f32 v[36:37], v[36:37], v[170:171], v[246:247]
	v_pk_fma_f32 v[34:35], v[34:35], v[168:169], v[244:245]
	global_store_dwordx4 v157, v[34:37], s[76:77] offset:576
	global_load_dwordx4 v[244:247], v157, s[74:75] offset:64 nt
	s_add_u32 s76, s76, 0x20000
	s_addc_u32 s77, s77, 0
	s_waitcnt vmcnt(10)
	v_pk_fma_f32 v[32:33], v[32:33], v[142:143], v[226:227]
	v_pk_fma_f32 v[30:31], v[30:31], v[140:141], v[224:225]
	global_store_dwordx4 v157, v[30:33], s[76:77]
	global_load_dwordx4 v[224:227], v157, s[74:75] offset:512 nt
	s_waitcnt vmcnt(10)
	v_pk_fma_f32 v[28:29], v[28:29], v[146:147], v[230:231]
	v_pk_fma_f32 v[26:27], v[26:27], v[144:145], v[228:229]
	global_store_dwordx4 v157, v[26:29], s[76:77] offset:64
	global_load_dwordx4 v[228:231], v157, s[74:75] offset:576 nt
	s_waitcnt vmcnt(10)
	v_pk_fma_f32 v[24:25], v[24:25], v[150:151], v[234:235]
	v_pk_fma_f32 v[22:23], v[22:23], v[148:149], v[232:233]
	global_store_dwordx4 v157, v[22:25], s[76:77] offset:512
	s_waitcnt vmcnt(9)
	v_pk_fma_f32 v[20:21], v[20:21], v[170:171], v[238:239]
	v_pk_fma_f32 v[18:19], v[18:19], v[168:169], v[236:237]
	global_store_dwordx4 v157, v[18:21], s[76:77] offset:576
	s_add_u32 s76, s76, 0x20000
	s_addc_u32 s77, s77, 0
	s_waitcnt vmcnt(8)
	v_pk_fma_f32 v[16:17], v[16:17], v[142:143], v[242:243]
	v_pk_fma_f32 v[14:15], v[14:15], v[140:141], v[240:241]
	global_store_dwordx4 v157, v[14:17], s[76:77]
	s_waitcnt vmcnt(7)
	v_pk_fma_f32 v[12:13], v[12:13], v[146:147], v[246:247]
	v_pk_fma_f32 v[10:11], v[10:11], v[144:145], v[244:245]
	global_store_dwordx4 v157, v[10:13], s[76:77] offset:64
	s_waitcnt vmcnt(6)
	v_pk_fma_f32 v[8:9], v[8:9], v[150:151], v[226:227]
	v_pk_fma_f32 v[6:7], v[6:7], v[148:149], v[224:225]
	global_store_dwordx4 v157, v[6:9], s[76:77] offset:512
	s_waitcnt vmcnt(5)
	v_pk_fma_f32 v[4:5], v[4:5], v[170:171], v[230:231]
	v_pk_fma_f32 v[2:3], v[2:3], v[168:169], v[228:229]
	global_store_dwordx4 v157, v[2:5], s[76:77] offset:576
	s_branch .LBB0_269

.LBB0_572:
	s_add_u32 s41, s46, 0xfff80080
	s_addc_u32 s48, s47, -1
	s_add_i32 s64, 0, 0x10000
	ds_read_b128 v[144:147], v141
	ds_read_b128 v[148:151], v141 offset:1024
	ds_read_b128 v[152:155], v141 offset:2048
	ds_read_b128 v[168:171], v141 offset:3072
	s_cmp_eq_u32 s39, 28
	s_cselect_b32 s51, s43, s48
	s_cselect_b32 s50, s42, s41
	s_cselect_b32 s49, s45, s13
	s_cselect_b32 s48, s44, s12
	ds_read_b128 v[172:175], v143
	ds_read_b128 v[176:179], v143 offset:1024
	ds_read_b128 v[180:183], v143 offset:2048
	ds_read_b128 v[184:187], v143 offset:3072
	ds_read_b128 v[188:191], v143 offset:4096
	ds_read_b128 v[192:195], v143 offset:5120
	ds_read_b128 v[196:199], v143 offset:6144
	ds_read_b128 v[224:227], v143 offset:7168
	s_add_i32 m0, s54, 0xc000
	s_nop 0
	global_load_lds_dwordx4 v136, s[46:47]
	s_add_i32 m0, s54, 0xe000
	s_add_i32 s41, 0, 0x14000
	global_load_lds_dwordx4 v138, s[46:47]
	s_add_i32 s64, s64, s53
	ds_read_b128 v[228:231], v141 offset:16384
	ds_read_b128 v[232:235], v141 offset:17408
	ds_read_b128 v[236:239], v141 offset:18432
	ds_read_b128 v[240:243], v141 offset:19456
	s_waitcnt lgkmcnt(0)
	s_barrier
	v_mfma_f32_16x16x32_bf16 v[126:129], v[144:147], v[172:175], v[126:129]
	v_mfma_f32_16x16x32_bf16 v[122:125], v[152:155], v[172:175], v[122:125]
	v_mfma_f32_16x16x32_bf16 v[118:121], v[144:147], v[180:183], v[118:121]
	v_mfma_f32_16x16x32_bf16 v[114:117], v[152:155], v[180:183], v[114:117]
	v_mfma_f32_16x16x32_bf16 v[102:105], v[144:147], v[188:191], v[102:105]
	v_mfma_f32_16x16x32_bf16 v[98:101], v[152:155], v[188:191], v[98:101]
	v_mfma_f32_16x16x32_bf16 v[86:89], v[144:147], v[196:199], v[86:89]
	v_mfma_f32_16x16x32_bf16 v[82:85], v[152:155], v[196:199], v[82:85]
	v_mfma_f32_16x16x32_bf16 v[126:129], v[148:151], v[176:179], v[126:129]
	v_mfma_f32_16x16x32_bf16 v[122:125], v[168:171], v[176:179], v[122:125]
	v_mfma_f32_16x16x32_bf16 v[118:121], v[148:151], v[184:187], v[118:121]
	v_mfma_f32_16x16x32_bf16 v[114:117], v[168:171], v[184:187], v[114:117]
	v_mfma_f32_16x16x32_bf16 v[102:105], v[148:151], v[192:195], v[102:105]
	v_mfma_f32_16x16x32_bf16 v[98:101], v[168:171], v[192:195], v[98:101]
	v_mfma_f32_16x16x32_bf16 v[86:89], v[148:151], v[224:227], v[86:89]
	v_mfma_f32_16x16x32_bf16 v[82:85], v[168:171], v[224:227], v[82:85]
	v_mfma_f32_16x16x32_bf16 v[110:113], v[228:231], v[172:175], v[110:113]
	v_mfma_f32_16x16x32_bf16 v[106:109], v[236:239], v[172:175], v[106:109]
	v_mfma_f32_16x16x32_bf16 v[94:97], v[228:231], v[180:183], v[94:97]
	v_mfma_f32_16x16x32_bf16 v[90:93], v[236:239], v[180:183], v[90:93]
	v_mfma_f32_16x16x32_bf16 v[78:81], v[228:231], v[188:191], v[78:81]
	v_mfma_f32_16x16x32_bf16 v[74:77], v[236:239], v[188:191], v[74:77]
	v_mfma_f32_16x16x32_bf16 v[70:73], v[228:231], v[196:199], v[70:73]
	v_mfma_f32_16x16x32_bf16 v[66:69], v[236:239], v[196:199], v[66:69]
	v_mfma_f32_16x16x32_bf16 v[110:113], v[232:235], v[176:179], v[110:113]
	v_mfma_f32_16x16x32_bf16 v[106:109], v[240:243], v[176:179], v[106:109]
	v_mfma_f32_16x16x32_bf16 v[94:97], v[232:235], v[184:187], v[94:97]
	v_mfma_f32_16x16x32_bf16 v[90:93], v[240:243], v[184:187], v[90:93]
	v_mfma_f32_16x16x32_bf16 v[78:81], v[232:235], v[192:195], v[78:81]
	v_mfma_f32_16x16x32_bf16 v[74:77], v[240:243], v[192:195], v[74:77]
	v_mfma_f32_16x16x32_bf16 v[70:73], v[232:235], v[224:227], v[70:73]
	v_mfma_f32_16x16x32_bf16 v[66:69], v[240:243], v[224:227], v[66:69]
	s_barrier
	s_mov_b32 m0, s54
	s_add_u32 s78, s50, s94
	s_addc_u32 s79, s51, s95
	ds_read_b128 v[172:175], v143 offset:16384
	ds_read_b128 v[176:179], v143 offset:17408
	ds_read_b128 v[180:183], v143 offset:18432
	ds_read_b128 v[184:187], v143 offset:19456
	ds_read_b128 v[188:191], v143 offset:20480
	ds_read_b128 v[192:195], v143 offset:21504
	ds_read_b128 v[196:199], v143 offset:22528
	ds_read_b128 v[224:227], v143 offset:23552
	global_load_lds_dwordx4 v130, s[50:51]
	s_mov_b32 m0, s55
	s_add_u32 s76, s48, s94
	s_addc_u32 s77, s49, s95
	global_load_lds_dwordx4 v132, s[50:51]
	s_mov_b32 m0, s64
	s_nop 0
	global_load_lds_dwordx4 v0, s[48:49]
	s_add_i32 m0, s64, 0x2000
	s_add_u32 s64, s48, 0x80000
	s_addc_u32 s65, s49, 0
	global_load_lds_dwordx4 v134, s[48:49]
	s_add_i32 s41, s41, s53
	s_mov_b32 m0, s41
	s_nop 0
	global_load_lds_dwordx4 v0, s[64:65]
	s_add_i32 m0, s41, 0x2000
	s_nop 0
	global_load_lds_dwordx4 v134, s[64:65]
	s_waitcnt vmcnt(6) lgkmcnt(0)
	s_barrier
	v_mfma_f32_16x16x32_bf16 v[62:65], v[144:147], v[172:175], v[62:65]
	v_mfma_f32_16x16x32_bf16 v[58:61], v[152:155], v[172:175], v[58:61]
	v_mfma_f32_16x16x32_bf16 v[54:57], v[144:147], v[180:183], v[54:57]
	v_mfma_f32_16x16x32_bf16 v[50:53], v[152:155], v[180:183], v[50:53]
	v_mfma_f32_16x16x32_bf16 v[38:41], v[144:147], v[188:191], v[38:41]
	v_mfma_f32_16x16x32_bf16 v[34:37], v[152:155], v[188:191], v[34:37]
	v_mfma_f32_16x16x32_bf16 v[22:25], v[144:147], v[196:199], v[22:25]
	v_mfma_f32_16x16x32_bf16 v[18:21], v[152:155], v[196:199], v[18:21]
	v_mfma_f32_16x16x32_bf16 v[62:65], v[148:151], v[176:179], v[62:65]
	v_mfma_f32_16x16x32_bf16 v[58:61], v[168:171], v[176:179], v[58:61]
	v_mfma_f32_16x16x32_bf16 v[54:57], v[148:151], v[184:187], v[54:57]
	v_mfma_f32_16x16x32_bf16 v[50:53], v[168:171], v[184:187], v[50:53]
	v_mfma_f32_16x16x32_bf16 v[38:41], v[148:151], v[192:195], v[38:41]
	v_mfma_f32_16x16x32_bf16 v[34:37], v[168:171], v[192:195], v[34:37]
	v_mfma_f32_16x16x32_bf16 v[22:25], v[148:151], v[224:227], v[22:25]
	v_mfma_f32_16x16x32_bf16 v[18:21], v[168:171], v[224:227], v[18:21]
	v_mfma_f32_16x16x32_bf16 v[46:49], v[228:231], v[172:175], v[46:49]
	v_mfma_f32_16x16x32_bf16 v[42:45], v[236:239], v[172:175], v[42:45]
	v_mfma_f32_16x16x32_bf16 v[30:33], v[228:231], v[180:183], v[30:33]
	v_mfma_f32_16x16x32_bf16 v[26:29], v[236:239], v[180:183], v[26:29]
	v_mfma_f32_16x16x32_bf16 v[14:17], v[228:231], v[188:191], v[14:17]
	v_mfma_f32_16x16x32_bf16 v[10:13], v[236:239], v[188:191], v[10:13]
	v_mfma_f32_16x16x32_bf16 v[6:9], v[228:231], v[196:199], v[6:9]
	v_mfma_f32_16x16x32_bf16 v[2:5], v[236:239], v[196:199], v[2:5]
	v_mfma_f32_16x16x32_bf16 v[46:49], v[232:235], v[176:179], v[46:49]
	v_mfma_f32_16x16x32_bf16 v[42:45], v[240:243], v[176:179], v[42:45]
	v_mfma_f32_16x16x32_bf16 v[30:33], v[232:235], v[184:187], v[30:33]
	v_mfma_f32_16x16x32_bf16 v[26:29], v[240:243], v[184:187], v[26:29]
	v_mfma_f32_16x16x32_bf16 v[14:17], v[232:235], v[192:195], v[14:17]
	v_mfma_f32_16x16x32_bf16 v[10:13], v[240:243], v[192:195], v[10:13]
	v_mfma_f32_16x16x32_bf16 v[6:9], v[232:235], v[224:227], v[6:9]
	v_mfma_f32_16x16x32_bf16 v[2:5], v[240:243], v[224:227], v[2:5]
	s_barrier
	s_add_i32 s41, 0, 0x18000
	ds_read_b128 v[144:147], v141 offset:32768
	ds_read_b128 v[148:151], v141 offset:33792
	ds_read_b128 v[152:155], v141 offset:34816
	ds_read_b128 v[168:171], v141 offset:35840
	s_add_u32 s50, s50, 0x80000
	s_addc_u32 s51, s51, 0
	ds_read_b128 v[172:175], v143 offset:32768
	ds_read_b128 v[176:179], v143 offset:33792
	ds_read_b128 v[180:183], v143 offset:34816
	ds_read_b128 v[184:187], v143 offset:35840
	ds_read_b128 v[188:191], v143 offset:36864
	ds_read_b128 v[192:195], v143 offset:37888
	ds_read_b128 v[196:199], v143 offset:38912
	ds_read_b128 v[224:227], v143 offset:39936
	s_mov_b32 m0, s56
	s_nop 0
	global_load_lds_dwordx4 v130, s[50:51]
	s_mov_b32 m0, s57
	s_nop 0
	global_load_lds_dwordx4 v132, s[50:51]
	s_add_i32 s50, 0, 0x1c000
	s_add_i32 s41, s41, s53
	ds_read_b128 v[228:231], v141 offset:49152
	ds_read_b128 v[232:235], v141 offset:50176
	ds_read_b128 v[236:239], v141 offset:51200
	ds_read_b128 v[240:243], v141 offset:52224
	s_waitcnt lgkmcnt(0)
	s_nop 0
	s_barrier
	v_mfma_f32_16x16x32_bf16 v[126:129], v[144:147], v[172:175], v[126:129]
	v_mfma_f32_16x16x32_bf16 v[122:125], v[152:155], v[172:175], v[122:125]
	v_mfma_f32_16x16x32_bf16 v[118:121], v[144:147], v[180:183], v[118:121]
	v_mfma_f32_16x16x32_bf16 v[114:117], v[152:155], v[180:183], v[114:117]
	v_mfma_f32_16x16x32_bf16 v[102:105], v[144:147], v[188:191], v[102:105]
	v_mfma_f32_16x16x32_bf16 v[98:101], v[152:155], v[188:191], v[98:101]
	v_mfma_f32_16x16x32_bf16 v[86:89], v[144:147], v[196:199], v[86:89]
	v_mfma_f32_16x16x32_bf16 v[82:85], v[152:155], v[196:199], v[82:85]
	v_mfma_f32_16x16x32_bf16 v[126:129], v[148:151], v[176:179], v[126:129]
	v_mfma_f32_16x16x32_bf16 v[122:125], v[168:171], v[176:179], v[122:125]
	v_mfma_f32_16x16x32_bf16 v[118:121], v[148:151], v[184:187], v[118:121]
	v_mfma_f32_16x16x32_bf16 v[114:117], v[168:171], v[184:187], v[114:117]
	v_mfma_f32_16x16x32_bf16 v[102:105], v[148:151], v[192:195], v[102:105]
	v_mfma_f32_16x16x32_bf16 v[98:101], v[168:171], v[192:195], v[98:101]
	v_mfma_f32_16x16x32_bf16 v[86:89], v[148:151], v[224:227], v[86:89]
	v_mfma_f32_16x16x32_bf16 v[82:85], v[168:171], v[224:227], v[82:85]
	v_mfma_f32_16x16x32_bf16 v[110:113], v[228:231], v[172:175], v[110:113]
	v_mfma_f32_16x16x32_bf16 v[106:109], v[236:239], v[172:175], v[106:109]
	v_mfma_f32_16x16x32_bf16 v[94:97], v[228:231], v[180:183], v[94:97]
	v_mfma_f32_16x16x32_bf16 v[90:93], v[236:239], v[180:183], v[90:93]
	v_mfma_f32_16x16x32_bf16 v[78:81], v[228:231], v[188:191], v[78:81]
	v_mfma_f32_16x16x32_bf16 v[74:77], v[236:239], v[188:191], v[74:77]
	v_mfma_f32_16x16x32_bf16 v[70:73], v[228:231], v[196:199], v[70:73]
	v_mfma_f32_16x16x32_bf16 v[66:69], v[236:239], v[196:199], v[66:69]
	v_mfma_f32_16x16x32_bf16 v[110:113], v[232:235], v[176:179], v[110:113]
	v_mfma_f32_16x16x32_bf16 v[106:109], v[240:243], v[176:179], v[106:109]
	v_mfma_f32_16x16x32_bf16 v[94:97], v[232:235], v[184:187], v[94:97]
	v_mfma_f32_16x16x32_bf16 v[90:93], v[240:243], v[184:187], v[90:93]
	v_mfma_f32_16x16x32_bf16 v[78:81], v[232:235], v[192:195], v[78:81]
	v_mfma_f32_16x16x32_bf16 v[74:77], v[240:243], v[192:195], v[74:77]
	v_mfma_f32_16x16x32_bf16 v[70:73], v[232:235], v[224:227], v[70:73]
	v_mfma_f32_16x16x32_bf16 v[66:69], v[240:243], v[224:227], v[66:69]
	s_barrier
	s_mov_b32 m0, s59
	ds_read_b128 v[172:175], v143 offset:49152
	ds_read_b128 v[176:179], v143 offset:50176
	ds_read_b128 v[180:183], v143 offset:51200
	ds_read_b128 v[184:187], v143 offset:52224
	ds_read_b128 v[188:191], v143 offset:53248
	ds_read_b128 v[192:195], v143 offset:54272
	ds_read_b128 v[196:199], v143 offset:55296
	ds_read_b128 v[224:227], v143 offset:56320
	global_load_lds_dwordx4 v130, s[78:79]
	s_mov_b32 m0, s60
	s_nop 0
	global_load_lds_dwordx4 v132, s[78:79]
	s_mov_b32 m0, s41
	s_nop 0
	global_load_lds_dwordx4 v0, s[76:77]
	s_add_i32 m0, s41, 0x2000
	s_add_u32 s48, s48, 0x80080
	s_addc_u32 s49, s49, 0
	global_load_lds_dwordx4 v134, s[76:77]
	s_add_i32 s41, s50, s53
	s_mov_b32 m0, s41
	s_nop 0
	global_load_lds_dwordx4 v0, s[48:49]
	s_add_i32 m0, s41, 0x2000
	s_nop 0
	global_load_lds_dwordx4 v134, s[48:49]
	s_waitcnt vmcnt(6) lgkmcnt(0)
	s_nop 0
	s_barrier
	v_mfma_f32_16x16x32_bf16 v[62:65], v[144:147], v[172:175], v[62:65]
	v_mfma_f32_16x16x32_bf16 v[58:61], v[152:155], v[172:175], v[58:61]
	v_mfma_f32_16x16x32_bf16 v[54:57], v[144:147], v[180:183], v[54:57]
	v_mfma_f32_16x16x32_bf16 v[50:53], v[152:155], v[180:183], v[50:53]
	v_mfma_f32_16x16x32_bf16 v[38:41], v[144:147], v[188:191], v[38:41]
	v_mfma_f32_16x16x32_bf16 v[34:37], v[152:155], v[188:191], v[34:37]
	v_mfma_f32_16x16x32_bf16 v[22:25], v[144:147], v[196:199], v[22:25]
	v_mfma_f32_16x16x32_bf16 v[18:21], v[152:155], v[196:199], v[18:21]
	v_mfma_f32_16x16x32_bf16 v[62:65], v[148:151], v[176:179], v[62:65]
	v_mfma_f32_16x16x32_bf16 v[58:61], v[168:171], v[176:179], v[58:61]
	v_mfma_f32_16x16x32_bf16 v[54:57], v[148:151], v[184:187], v[54:57]
	v_mfma_f32_16x16x32_bf16 v[50:53], v[168:171], v[184:187], v[50:53]
	v_mfma_f32_16x16x32_bf16 v[38:41], v[148:151], v[192:195], v[38:41]
	v_mfma_f32_16x16x32_bf16 v[34:37], v[168:171], v[192:195], v[34:37]
	v_mfma_f32_16x16x32_bf16 v[22:25], v[148:151], v[224:227], v[22:25]
	v_mfma_f32_16x16x32_bf16 v[18:21], v[168:171], v[224:227], v[18:21]
	v_mfma_f32_16x16x32_bf16 v[46:49], v[228:231], v[172:175], v[46:49]
	v_mfma_f32_16x16x32_bf16 v[42:45], v[236:239], v[172:175], v[42:45]
	v_mfma_f32_16x16x32_bf16 v[30:33], v[228:231], v[180:183], v[30:33]
	v_mfma_f32_16x16x32_bf16 v[26:29], v[236:239], v[180:183], v[26:29]
	v_mfma_f32_16x16x32_bf16 v[14:17], v[228:231], v[188:191], v[14:17]
	v_mfma_f32_16x16x32_bf16 v[10:13], v[236:239], v[188:191], v[10:13]
	v_mfma_f32_16x16x32_bf16 v[6:9], v[228:231], v[196:199], v[6:9]
	v_mfma_f32_16x16x32_bf16 v[2:5], v[236:239], v[196:199], v[2:5]
	v_mfma_f32_16x16x32_bf16 v[46:49], v[232:235], v[176:179], v[46:49]
	v_mfma_f32_16x16x32_bf16 v[42:45], v[240:243], v[176:179], v[42:45]
	v_mfma_f32_16x16x32_bf16 v[30:33], v[232:235], v[184:187], v[30:33]
	v_mfma_f32_16x16x32_bf16 v[26:29], v[240:243], v[184:187], v[26:29]
	v_mfma_f32_16x16x32_bf16 v[14:17], v[232:235], v[192:195], v[14:17]
	v_mfma_f32_16x16x32_bf16 v[10:13], v[240:243], v[192:195], v[10:13]
	v_mfma_f32_16x16x32_bf16 v[6:9], v[232:235], v[224:227], v[6:9]
	v_mfma_f32_16x16x32_bf16 v[2:5], v[240:243], v[224:227], v[2:5]
	s_barrier
	s_add_i32 s39, s39, 2
	s_add_u32 s46, s46, 0x100
	s_addc_u32 s47, s47, 0
	s_add_u32 s12, s12, 0x100
	s_addc_u32 s13, s13, 0
	s_cmp_gt_u32 s39, 29
	s_cbranch_scc0 .LBB0_572
	s_cmp_lg_u32 s62, 0
	s_cbranch_scc0 .LBB0_575
	s_lshl_b32 s39, s61, 8
	s_mov_b64 s[12:13], 0
	s_branch .LBB0_576

.LBB0_788:
	s_add_u32 s39, s46, 0xfff80080
	s_addc_u32 s48, s47, -1
	s_add_i32 s64, 0, 0x10000
	ds_read_b128 v[144:147], v141
	ds_read_b128 v[148:151], v141 offset:1024
	ds_read_b128 v[152:155], v141 offset:2048
	ds_read_b128 v[168:171], v141 offset:3072
	s_cmp_eq_u32 s13, 28
	s_cselect_b32 s51, s43, s48
	s_cselect_b32 s50, s42, s39
	s_cselect_b32 s49, s45, s12
	s_cselect_b32 s48, s44, s1
	ds_read_b128 v[172:175], v143
	ds_read_b128 v[176:179], v143 offset:1024
	ds_read_b128 v[180:183], v143 offset:2048
	ds_read_b128 v[184:187], v143 offset:3072
	ds_read_b128 v[188:191], v143 offset:4096
	ds_read_b128 v[192:195], v143 offset:5120
	ds_read_b128 v[196:199], v143 offset:6144
	ds_read_b128 v[224:227], v143 offset:7168
	s_add_i32 m0, s54, 0xc000
	s_nop 0
	global_load_lds_dwordx4 v136, s[46:47]
	s_add_i32 m0, s54, 0xe000
	s_add_i32 s39, 0, 0x14000
	global_load_lds_dwordx4 v138, s[46:47]
	s_add_i32 s64, s64, s53
	ds_read_b128 v[228:231], v141 offset:16384
	ds_read_b128 v[232:235], v141 offset:17408
	ds_read_b128 v[236:239], v141 offset:18432
	ds_read_b128 v[240:243], v141 offset:19456
	s_waitcnt lgkmcnt(0)
	s_nop 0
	s_barrier
	v_mfma_f32_16x16x32_bf16 v[126:129], v[144:147], v[172:175], v[126:129]
	v_mfma_f32_16x16x32_bf16 v[122:125], v[152:155], v[172:175], v[122:125]
	v_mfma_f32_16x16x32_bf16 v[118:121], v[144:147], v[180:183], v[118:121]
	v_mfma_f32_16x16x32_bf16 v[114:117], v[152:155], v[180:183], v[114:117]
	v_mfma_f32_16x16x32_bf16 v[102:105], v[144:147], v[188:191], v[102:105]
	v_mfma_f32_16x16x32_bf16 v[98:101], v[152:155], v[188:191], v[98:101]
	v_mfma_f32_16x16x32_bf16 v[86:89], v[144:147], v[196:199], v[86:89]
	v_mfma_f32_16x16x32_bf16 v[82:85], v[152:155], v[196:199], v[82:85]
	v_mfma_f32_16x16x32_bf16 v[126:129], v[148:151], v[176:179], v[126:129]
	v_mfma_f32_16x16x32_bf16 v[122:125], v[168:171], v[176:179], v[122:125]
	v_mfma_f32_16x16x32_bf16 v[118:121], v[148:151], v[184:187], v[118:121]
	v_mfma_f32_16x16x32_bf16 v[114:117], v[168:171], v[184:187], v[114:117]
	v_mfma_f32_16x16x32_bf16 v[102:105], v[148:151], v[192:195], v[102:105]
	v_mfma_f32_16x16x32_bf16 v[98:101], v[168:171], v[192:195], v[98:101]
	v_mfma_f32_16x16x32_bf16 v[86:89], v[148:151], v[224:227], v[86:89]
	v_mfma_f32_16x16x32_bf16 v[82:85], v[168:171], v[224:227], v[82:85]
	v_mfma_f32_16x16x32_bf16 v[110:113], v[228:231], v[172:175], v[110:113]
	v_mfma_f32_16x16x32_bf16 v[106:109], v[236:239], v[172:175], v[106:109]
	v_mfma_f32_16x16x32_bf16 v[94:97], v[228:231], v[180:183], v[94:97]
	v_mfma_f32_16x16x32_bf16 v[90:93], v[236:239], v[180:183], v[90:93]
	v_mfma_f32_16x16x32_bf16 v[78:81], v[228:231], v[188:191], v[78:81]
	v_mfma_f32_16x16x32_bf16 v[74:77], v[236:239], v[188:191], v[74:77]
	v_mfma_f32_16x16x32_bf16 v[70:73], v[228:231], v[196:199], v[70:73]
	v_mfma_f32_16x16x32_bf16 v[66:69], v[236:239], v[196:199], v[66:69]
	v_mfma_f32_16x16x32_bf16 v[110:113], v[232:235], v[176:179], v[110:113]
	v_mfma_f32_16x16x32_bf16 v[106:109], v[240:243], v[176:179], v[106:109]
	v_mfma_f32_16x16x32_bf16 v[94:97], v[232:235], v[184:187], v[94:97]
	v_mfma_f32_16x16x32_bf16 v[90:93], v[240:243], v[184:187], v[90:93]
	v_mfma_f32_16x16x32_bf16 v[78:81], v[232:235], v[192:195], v[78:81]
	v_mfma_f32_16x16x32_bf16 v[74:77], v[240:243], v[192:195], v[74:77]
	v_mfma_f32_16x16x32_bf16 v[70:73], v[232:235], v[224:227], v[70:73]
	v_mfma_f32_16x16x32_bf16 v[66:69], v[240:243], v[224:227], v[66:69]
	s_barrier
	s_mov_b32 m0, s54
	s_add_u32 s78, s50, s94
	s_addc_u32 s79, s51, s95
	ds_read_b128 v[172:175], v143 offset:16384
	ds_read_b128 v[176:179], v143 offset:17408
	ds_read_b128 v[180:183], v143 offset:18432
	ds_read_b128 v[184:187], v143 offset:19456
	ds_read_b128 v[188:191], v143 offset:20480
	ds_read_b128 v[192:195], v143 offset:21504
	ds_read_b128 v[196:199], v143 offset:22528
	ds_read_b128 v[224:227], v143 offset:23552
	global_load_lds_dwordx4 v130, s[50:51]
	s_mov_b32 m0, s55
	s_add_u32 s76, s48, s94
	s_addc_u32 s77, s49, s95
	global_load_lds_dwordx4 v132, s[50:51]
	s_mov_b32 m0, s64
	s_nop 0
	global_load_lds_dwordx4 v0, s[48:49]
	s_add_i32 m0, s64, 0x2000
	s_add_u32 s64, s48, 0x80000
	s_addc_u32 s65, s49, 0
	global_load_lds_dwordx4 v134, s[48:49]
	s_add_i32 s39, s39, s53
	s_mov_b32 m0, s39
	s_nop 0
	global_load_lds_dwordx4 v0, s[64:65]
	s_add_i32 m0, s39, 0x2000
	s_nop 0
	global_load_lds_dwordx4 v134, s[64:65]
	s_waitcnt vmcnt(6) lgkmcnt(0)
	s_barrier
	v_mfma_f32_16x16x32_bf16 v[62:65], v[144:147], v[172:175], v[62:65]
	v_mfma_f32_16x16x32_bf16 v[58:61], v[152:155], v[172:175], v[58:61]
	v_mfma_f32_16x16x32_bf16 v[54:57], v[144:147], v[180:183], v[54:57]
	v_mfma_f32_16x16x32_bf16 v[50:53], v[152:155], v[180:183], v[50:53]
	v_mfma_f32_16x16x32_bf16 v[38:41], v[144:147], v[188:191], v[38:41]
	v_mfma_f32_16x16x32_bf16 v[34:37], v[152:155], v[188:191], v[34:37]
	v_mfma_f32_16x16x32_bf16 v[22:25], v[144:147], v[196:199], v[22:25]
	v_mfma_f32_16x16x32_bf16 v[18:21], v[152:155], v[196:199], v[18:21]
	v_mfma_f32_16x16x32_bf16 v[62:65], v[148:151], v[176:179], v[62:65]
	v_mfma_f32_16x16x32_bf16 v[58:61], v[168:171], v[176:179], v[58:61]
	v_mfma_f32_16x16x32_bf16 v[54:57], v[148:151], v[184:187], v[54:57]
	v_mfma_f32_16x16x32_bf16 v[50:53], v[168:171], v[184:187], v[50:53]
	v_mfma_f32_16x16x32_bf16 v[38:41], v[148:151], v[192:195], v[38:41]
	v_mfma_f32_16x16x32_bf16 v[34:37], v[168:171], v[192:195], v[34:37]
	v_mfma_f32_16x16x32_bf16 v[22:25], v[148:151], v[224:227], v[22:25]
	v_mfma_f32_16x16x32_bf16 v[18:21], v[168:171], v[224:227], v[18:21]
	v_mfma_f32_16x16x32_bf16 v[46:49], v[228:231], v[172:175], v[46:49]
	v_mfma_f32_16x16x32_bf16 v[42:45], v[236:239], v[172:175], v[42:45]
	v_mfma_f32_16x16x32_bf16 v[30:33], v[228:231], v[180:183], v[30:33]
	v_mfma_f32_16x16x32_bf16 v[26:29], v[236:239], v[180:183], v[26:29]
	v_mfma_f32_16x16x32_bf16 v[14:17], v[228:231], v[188:191], v[14:17]
	v_mfma_f32_16x16x32_bf16 v[10:13], v[236:239], v[188:191], v[10:13]
	v_mfma_f32_16x16x32_bf16 v[6:9], v[228:231], v[196:199], v[6:9]
	v_mfma_f32_16x16x32_bf16 v[2:5], v[236:239], v[196:199], v[2:5]
	v_mfma_f32_16x16x32_bf16 v[46:49], v[232:235], v[176:179], v[46:49]
	v_mfma_f32_16x16x32_bf16 v[42:45], v[240:243], v[176:179], v[42:45]
	v_mfma_f32_16x16x32_bf16 v[30:33], v[232:235], v[184:187], v[30:33]
	v_mfma_f32_16x16x32_bf16 v[26:29], v[240:243], v[184:187], v[26:29]
	v_mfma_f32_16x16x32_bf16 v[14:17], v[232:235], v[192:195], v[14:17]
	v_mfma_f32_16x16x32_bf16 v[10:13], v[240:243], v[192:195], v[10:13]
	v_mfma_f32_16x16x32_bf16 v[6:9], v[232:235], v[224:227], v[6:9]
	v_mfma_f32_16x16x32_bf16 v[2:5], v[240:243], v[224:227], v[2:5]
	s_barrier
	s_add_i32 s39, 0, 0x18000
	ds_read_b128 v[144:147], v141 offset:32768
	ds_read_b128 v[148:151], v141 offset:33792
	ds_read_b128 v[152:155], v141 offset:34816
	ds_read_b128 v[168:171], v141 offset:35840
	s_add_u32 s50, s50, 0x80000
	s_addc_u32 s51, s51, 0
	ds_read_b128 v[172:175], v143 offset:32768
	ds_read_b128 v[176:179], v143 offset:33792
	ds_read_b128 v[180:183], v143 offset:34816
	ds_read_b128 v[184:187], v143 offset:35840
	ds_read_b128 v[188:191], v143 offset:36864
	ds_read_b128 v[192:195], v143 offset:37888
	ds_read_b128 v[196:199], v143 offset:38912
	ds_read_b128 v[224:227], v143 offset:39936
	s_mov_b32 m0, s56
	s_nop 0
	global_load_lds_dwordx4 v130, s[50:51]
	s_mov_b32 m0, s57
	s_nop 0
	global_load_lds_dwordx4 v132, s[50:51]
	s_add_i32 s50, 0, 0x1c000
	s_add_i32 s39, s39, s53
	ds_read_b128 v[228:231], v141 offset:49152
	ds_read_b128 v[232:235], v141 offset:50176
	ds_read_b128 v[236:239], v141 offset:51200
	ds_read_b128 v[240:243], v141 offset:52224
	s_waitcnt lgkmcnt(0)
	s_nop 0
	s_barrier
	v_mfma_f32_16x16x32_bf16 v[126:129], v[144:147], v[172:175], v[126:129]
	v_mfma_f32_16x16x32_bf16 v[122:125], v[152:155], v[172:175], v[122:125]
	v_mfma_f32_16x16x32_bf16 v[118:121], v[144:147], v[180:183], v[118:121]
	v_mfma_f32_16x16x32_bf16 v[114:117], v[152:155], v[180:183], v[114:117]
	v_mfma_f32_16x16x32_bf16 v[102:105], v[144:147], v[188:191], v[102:105]
	v_mfma_f32_16x16x32_bf16 v[98:101], v[152:155], v[188:191], v[98:101]
	v_mfma_f32_16x16x32_bf16 v[86:89], v[144:147], v[196:199], v[86:89]
	v_mfma_f32_16x16x32_bf16 v[82:85], v[152:155], v[196:199], v[82:85]
	v_mfma_f32_16x16x32_bf16 v[126:129], v[148:151], v[176:179], v[126:129]
	v_mfma_f32_16x16x32_bf16 v[122:125], v[168:171], v[176:179], v[122:125]
	v_mfma_f32_16x16x32_bf16 v[118:121], v[148:151], v[184:187], v[118:121]
	v_mfma_f32_16x16x32_bf16 v[114:117], v[168:171], v[184:187], v[114:117]
	v_mfma_f32_16x16x32_bf16 v[102:105], v[148:151], v[192:195], v[102:105]
	v_mfma_f32_16x16x32_bf16 v[98:101], v[168:171], v[192:195], v[98:101]
	v_mfma_f32_16x16x32_bf16 v[86:89], v[148:151], v[224:227], v[86:89]
	v_mfma_f32_16x16x32_bf16 v[82:85], v[168:171], v[224:227], v[82:85]
	v_mfma_f32_16x16x32_bf16 v[110:113], v[228:231], v[172:175], v[110:113]
	v_mfma_f32_16x16x32_bf16 v[106:109], v[236:239], v[172:175], v[106:109]
	v_mfma_f32_16x16x32_bf16 v[94:97], v[228:231], v[180:183], v[94:97]
	v_mfma_f32_16x16x32_bf16 v[90:93], v[236:239], v[180:183], v[90:93]
	v_mfma_f32_16x16x32_bf16 v[78:81], v[228:231], v[188:191], v[78:81]
	v_mfma_f32_16x16x32_bf16 v[74:77], v[236:239], v[188:191], v[74:77]
	v_mfma_f32_16x16x32_bf16 v[70:73], v[228:231], v[196:199], v[70:73]
	v_mfma_f32_16x16x32_bf16 v[66:69], v[236:239], v[196:199], v[66:69]
	v_mfma_f32_16x16x32_bf16 v[110:113], v[232:235], v[176:179], v[110:113]
	v_mfma_f32_16x16x32_bf16 v[106:109], v[240:243], v[176:179], v[106:109]
	v_mfma_f32_16x16x32_bf16 v[94:97], v[232:235], v[184:187], v[94:97]
	v_mfma_f32_16x16x32_bf16 v[90:93], v[240:243], v[184:187], v[90:93]
	v_mfma_f32_16x16x32_bf16 v[78:81], v[232:235], v[192:195], v[78:81]
	v_mfma_f32_16x16x32_bf16 v[74:77], v[240:243], v[192:195], v[74:77]
	v_mfma_f32_16x16x32_bf16 v[70:73], v[232:235], v[224:227], v[70:73]
	v_mfma_f32_16x16x32_bf16 v[66:69], v[240:243], v[224:227], v[66:69]
	s_barrier
	s_mov_b32 m0, s59
	ds_read_b128 v[172:175], v143 offset:49152
	ds_read_b128 v[176:179], v143 offset:50176
	ds_read_b128 v[180:183], v143 offset:51200
	ds_read_b128 v[184:187], v143 offset:52224
	ds_read_b128 v[188:191], v143 offset:53248
	ds_read_b128 v[192:195], v143 offset:54272
	ds_read_b128 v[196:199], v143 offset:55296
	ds_read_b128 v[224:227], v143 offset:56320
	global_load_lds_dwordx4 v130, s[78:79]
	s_mov_b32 m0, s61
	s_nop 0
	global_load_lds_dwordx4 v132, s[78:79]
	s_mov_b32 m0, s39
	s_nop 0
	global_load_lds_dwordx4 v0, s[76:77]
	s_add_i32 m0, s39, 0x2000
	s_add_u32 s48, s48, 0x80080
	s_addc_u32 s49, s49, 0
	global_load_lds_dwordx4 v134, s[76:77]
	s_add_i32 s39, s50, s53
	s_mov_b32 m0, s39
	s_nop 0
	global_load_lds_dwordx4 v0, s[48:49]
	s_add_i32 m0, s39, 0x2000
	s_nop 0
	global_load_lds_dwordx4 v134, s[48:49]
	s_waitcnt vmcnt(6) lgkmcnt(0)
	s_nop 0
	s_barrier
	v_mfma_f32_16x16x32_bf16 v[62:65], v[144:147], v[172:175], v[62:65]
	v_mfma_f32_16x16x32_bf16 v[58:61], v[152:155], v[172:175], v[58:61]
	v_mfma_f32_16x16x32_bf16 v[54:57], v[144:147], v[180:183], v[54:57]
	v_mfma_f32_16x16x32_bf16 v[50:53], v[152:155], v[180:183], v[50:53]
	v_mfma_f32_16x16x32_bf16 v[38:41], v[144:147], v[188:191], v[38:41]
	v_mfma_f32_16x16x32_bf16 v[34:37], v[152:155], v[188:191], v[34:37]
	v_mfma_f32_16x16x32_bf16 v[22:25], v[144:147], v[196:199], v[22:25]
	v_mfma_f32_16x16x32_bf16 v[18:21], v[152:155], v[196:199], v[18:21]
	v_mfma_f32_16x16x32_bf16 v[62:65], v[148:151], v[176:179], v[62:65]
	v_mfma_f32_16x16x32_bf16 v[58:61], v[168:171], v[176:179], v[58:61]
	v_mfma_f32_16x16x32_bf16 v[54:57], v[148:151], v[184:187], v[54:57]
	v_mfma_f32_16x16x32_bf16 v[50:53], v[168:171], v[184:187], v[50:53]
	v_mfma_f32_16x16x32_bf16 v[38:41], v[148:151], v[192:195], v[38:41]
	v_mfma_f32_16x16x32_bf16 v[34:37], v[168:171], v[192:195], v[34:37]
	v_mfma_f32_16x16x32_bf16 v[22:25], v[148:151], v[224:227], v[22:25]
	v_mfma_f32_16x16x32_bf16 v[18:21], v[168:171], v[224:227], v[18:21]
	v_mfma_f32_16x16x32_bf16 v[46:49], v[228:231], v[172:175], v[46:49]
	v_mfma_f32_16x16x32_bf16 v[42:45], v[236:239], v[172:175], v[42:45]
	v_mfma_f32_16x16x32_bf16 v[30:33], v[228:231], v[180:183], v[30:33]
	v_mfma_f32_16x16x32_bf16 v[26:29], v[236:239], v[180:183], v[26:29]
	v_mfma_f32_16x16x32_bf16 v[14:17], v[228:231], v[188:191], v[14:17]
	v_mfma_f32_16x16x32_bf16 v[10:13], v[236:239], v[188:191], v[10:13]
	v_mfma_f32_16x16x32_bf16 v[6:9], v[228:231], v[196:199], v[6:9]
	v_mfma_f32_16x16x32_bf16 v[2:5], v[236:239], v[196:199], v[2:5]
	v_mfma_f32_16x16x32_bf16 v[46:49], v[232:235], v[176:179], v[46:49]
	v_mfma_f32_16x16x32_bf16 v[42:45], v[240:243], v[176:179], v[42:45]
	v_mfma_f32_16x16x32_bf16 v[30:33], v[232:235], v[184:187], v[30:33]
	v_mfma_f32_16x16x32_bf16 v[26:29], v[240:243], v[184:187], v[26:29]
	v_mfma_f32_16x16x32_bf16 v[14:17], v[232:235], v[192:195], v[14:17]
	v_mfma_f32_16x16x32_bf16 v[10:13], v[240:243], v[192:195], v[10:13]
	v_mfma_f32_16x16x32_bf16 v[6:9], v[232:235], v[224:227], v[6:9]
	v_mfma_f32_16x16x32_bf16 v[2:5], v[240:243], v[224:227], v[2:5]
	s_barrier
	s_add_i32 s13, s13, 2
	s_add_u32 s46, s46, 0x100
	s_addc_u32 s47, s47, 0
	s_add_u32 s1, s1, 0x100
	s_addc_u32 s12, s12, 0
	s_cmp_gt_u32 s13, 29
	s_cbranch_scc0 .LBB0_788
	s_cmp_lg_u32 s62, 0
	s_cbranch_scc0 .LBB0_791
	s_lshl_b32 s1, s60, 8
	s_mov_b64 s[12:13], 0
	s_branch .LBB0_792
